# v3 + phase0 tconv: loop-top waits no longer drain previous store; norm-gain loads hoisted before prefetch
# baseline (speedup 1.0000x reference)
; __device__ __forceinline__ int tid_v() { int t = threadIdx.x; asm volatile("" : "+v"(t)); return t; }
; __device__ __forceinline__ int bid_s() { int b = blockIdx.x; asm volatile("" : "+s"(b)); return b; }
; #define WSP() ((unsigned char*)karg_ptr<35 * 8>())
; __device__ __forceinline__ void tconv(const float* __restrict__ src, bf16_t* __restrict__ dst, int K, int N, const float* __restrict__ scale, float* tile, int& rot) {
;     const int tk = K >> 6, tn = N >> 6, nt = tk * tn, G = gridDim.x;
;     const int tid = tid_v(), lr = tid >> 4, lc = (tid & 15) * 4;
;     const int sn = tid >> 3, sk = (tid & 7) * 8;
;     int t = (int)((bid_s() + G - (rot % G)) % G);
;     f32x4 v0, v1;
;     if (t < nt) { const int kt = t / tn, k0 = kt << 6, n0 = (t - kt * tn) << 6; v0 = *(const f32x4*)(src + (size_t)(k0 + lr) * N + n0 + lc); v1 = *(const f32x4*)(src + (size_t)(k0 + lr + 32) * N + n0 + lc); }
; __device__ __forceinline__ void phase0(unsigned char* shm) {
;     ...
;         bf16_t* W = (bf16_t*)(WSP() + (size_t)l * WL_BYTES);
;         tconv(IN(3) + (size_t)l * 1024 * 8960, W + oWin, 1024, 8960, IN(2) + l * 1024, tile, rot);
.LBB0_7:
	s_load_dwordx2 s[10:11], s[0:1], 0x118
	s_waitcnt lgkmcnt(0)
	s_mul_i32 s3, s2, 0x2b00000
	s_mul_hi_u32 s20, s39, s36
	s_load_dwordx2 s[12:13], s[0:1], 24
	s_waitcnt lgkmcnt(0)
	s_add_u32 s10, s10, s3
	v_mov_b32_e32 v12, v179
	s_mov_b32 s3, s87
	s_mul_i32 s20, s20, s29
	s_load_dwordx2 s[18:19], s[0:1], 16
	s_waitcnt lgkmcnt(0)
	s_addc_u32 s11, s11, 0
	s_sub_i32 s20, s39, s20
	s_lshl_b32 s4, s2, 10
	s_add_i32 s3, s3, s72
	s_sub_i32 s21, s20, s29
	s_cmp_ge_u32 s20, s29
	s_cselect_b32 s20, s21, s20
	s_sub_i32 s21, s20, s29
	s_cmp_ge_u32 s20, s29
	s_cselect_b32 s20, s21, s20
	s_sub_i32 s20, s3, s20
	s_ashr_i32 s3, s20, 31
	s_abs_i32 s20, s20
	s_mul_hi_u32 s21, s20, s36
	s_mul_i32 s21, s21, s29
	s_sub_i32 s20, s20, s21
	s_sub_i32 s21, s20, s29
	s_cmp_ge_u32 s20, s29
	s_cselect_b32 s20, s21, s20
	s_sub_i32 s21, s20, s29
	s_cmp_ge_u32 s20, s29
	s_cselect_b32 s20, s21, s20
	s_xor_b32 s20, s20, s3
	s_sub_i32 s22, s20, s3
	s_cmpk_gt_i32 s22, 0x8bf
	s_cbranch_scc1 .LBB0_14
	s_mul_i32 s21, s2, 0x2300000
	s_add_u32 s12, s12, s21
	s_addc_u32 s13, s13, 0
	s_lshl_b64 s[24:25], s[4:5], 2
	s_add_u32 s24, s18, s24
	s_mul_hi_i32 s21, s22, 0xea0ea0eb
	s_addc_u32 s25, s19, s25
	s_add_i32 s21, s21, s22
	s_lshr_b32 s23, s21, 31
	s_ashr_i32 s21, s21, 7
	s_add_i32 s21, s21, s23
	s_mul_i32 s23, s21, 0x3ffff74
	s_add_i32 s23, s23, s22
	v_ashrrev_i32_e32 v1, 4, v12
	s_waitcnt vmcnt(2)
	v_lshlrev_b32_e32 v2, 2, v12
	s_lshl_b32 s26, s23, 6
	v_and_b32_e32 v14, 60, v2
	s_waitcnt vmcnt(1)
	v_lshl_add_u32 v6, s21, 6, v1
	v_mov_b64_e32 v[2:3], s[12:13]
	s_ashr_i32 s27, s26, 31
	v_mad_i64_i32 v[4:5], s[40:41], v6, s30, v[2:3]
	s_lshl_b64 s[26:27], s[26:27], 2
	v_lshl_add_u64 v[4:5], v[4:5], 0, s[26:27]
	v_lshlrev_b32_e32 v10, 2, v14
	v_lshl_add_u64 v[16:17], v[4:5], 0, v[10:11]
	v_add_u32_e32 v4, 32, v6
	v_mad_i64_i32 v[2:3], s[40:41], v4, s30, v[2:3]
	v_lshl_add_u64 v[2:3], v[2:3], 0, s[26:27]
	v_lshl_add_u64 v[18:19], v[2:3], 0, v[10:11]
	global_load_dwordx4 v[2:5], v[16:17], off
	global_load_dwordx4 v[6:9], v[18:19], off
	global_load_dword v52, v[16:17], off
	v_ashrrev_i32_e32 v24, 3, v12
	v_lshlrev_b32_e32 v12, 3, v12
	v_and_b32_e32 v16, 56, v12
	v_mul_lo_u32 v12, v1, s31
	v_add3_u32 v25, 0, v10, v12
	v_add3_u32 v15, 0, v12, v10
	v_lshlrev_b32_e32 v10, 2, v16
	v_lshl_add_u64 v[12:13], s[24:25], 0, v[10:11]
	v_mul_u32_u24_e32 v10, 0x41, v16
	v_lshlrev_b32_e32 v17, 2, v24
	s_cmp_lg_u64 s[18:19], 0
	v_lshlrev_b32_e32 v10, 2, v10
	s_cselect_b64 s[18:19], -1, 0
	v_add3_u32 v26, 0, v17, v10
	v_add3_u32 v17, 0, v10, v17
	s_lshl_b32 s20, s20, 6
	s_lshl_b32 s3, s3, 6
	s_sub_i32 s3, s20, s3
	v_add_u32_e32 v27, 0x2080, v15
	v_add_u32_e32 v28, 0x2088, v15
	v_lshlrev_b32_e32 v14, 2, v14
	v_lshlrev_b32_e32 v10, 1, v16
	v_add_u32_e32 v29, 0x400, v17
	s_branch .LBB0_10
.Ltc_drain_10:
	s_waitcnt vmcnt(0)
	s_branch .LBB0_12

; __device__ __forceinline__ u32x4 pack8(const f32x4& v0, const f32x4& v1) { u32x4 w; w.x = cvt_pk_bf16(v0[0], v0[1]); w.y = cvt_pk_bf16(v0[2], v0[3]); w.z = cvt_pk_bf16(v1[0], v1[1]); w.w = cvt_pk_bf16(v1[2], v1[3]); return w; }
; __device__ __forceinline__ void tconv(const float* __restrict__ src, bf16_t* __restrict__ dst, int K, int N, const float* __restrict__ scale, float* tile, int& rot) {
;     ...
;     for (; t < nt; t += G) {
;         const int kt = t / tn, k0 = kt << 6, n0 = (t - kt * tn) << 6;
;         __syncthreads();
; #pragma unroll
;         for (int j = 0; j < 4; ++j) { tile[lr * 65 + lc + j] = v0[j]; tile[(lr + 32) * 65 + lc + j] = v1[j]; }
;         const int t2 = t + G;
;         if (t2 < nt) { const int kt2 = t2 / tn, k2 = kt2 << 6, n2 = (t2 - kt2 * tn) << 6; v0 = *(const f32x4*)(src + (size_t)(k2 + lr) * N + n2 + lc); v1 = *(const f32x4*)(src + (size_t)(k2 + lr + 32) * N + n2 + lc); }
;         __syncthreads();
;         f32x4 a, bb;
; #pragma unroll
;         for (int j = 0; j < 4; ++j) { a[j] = tile[(sk + j) * 65 + sn]; bb[j] = tile[(sk + 4 + j) * 65 + sn]; }
;         if (scale) { a *= *(const f32x4*)(scale + k0 + sk); bb *= *(const f32x4*)(scale + k0 + sk + 4); }
;         *(u32x4*)(dst + (size_t)(n0 + sn) * K + k0 + sk) = pack8(a, bb);
;     }
; __device__ __forceinline__ void phase0(unsigned char* shm) {
;     ...
;         for (int k = 0; k < 4; ++k) tconv(IN(23) + (size_t)(l * 4 + k) * 512 * 1024, W + oWb + (size_t)k * 1024 * 512, 512, 1024, nullptr, tile, rot);
.LBB0_10:
	s_mul_hi_i32 s100, s22, 0xea0ea0eb
	s_add_i32 s100, s100, s22
	s_lshr_b32 s101, s100, 31
	s_ashr_i32 s100, s100, 7
	s_add_i32 s100, s100, s101
	s_lshl_b32 s100, s100, 6
	s_ashr_i32 s101, s100, 31
	v_lshl_add_u64 v[38:39], s[100:101], 2, v[12:13]
	global_load_dwordx4 v[30:33], v[38:39], off
	global_load_dwordx4 v[34:37], v[38:39], off offset:16
	s_add_i32 s24, s22, s72
	s_cmpk_gt_i32 s24, 0x8bf
	s_cselect_b64 s[20:21], -1, 0
	s_and_b64 vcc, exec, s[20:21]
	s_barrier
	s_waitcnt vmcnt(4)
	ds_write2_b32 v25, v2, v3 offset1:1
	s_waitcnt vmcnt(3)
	ds_write2_b32 v27, v6, v7 offset1:1
	ds_write2_b32 v25, v4, v5 offset0:2 offset1:3
	ds_write2_b32 v28, v8, v9 offset1:1
	s_cbranch_vccnz .Ltc_drain_10
	s_mul_hi_i32 s23, s24, 0xea0ea0eb
	s_add_i32 s23, s23, s24
	s_lshr_b32 s25, s23, 31
	s_ashr_i32 s23, s23, 7
	s_add_i32 s23, s23, s25
	s_mul_i32 s25, s23, 0xffffdd00
	s_add_i32 s26, s74, s3
	s_add_i32 s26, s26, s25
	v_lshl_add_u32 v6, s23, 6, v1
	v_mov_b64_e32 v[2:3], s[12:13]
	s_ashr_i32 s27, s26, 31
	v_mad_i64_i32 v[4:5], s[40:41], v6, s30, v[2:3]
	s_lshl_b64 s[26:27], s[26:27], 2
	v_lshl_add_u64 v[4:5], v[4:5], 0, s[26:27]
	v_mov_b32_e32 v15, v11
	v_lshl_add_u64 v[16:17], v[4:5], 0, v[14:15]
	v_add_u32_e32 v4, 32, v6
	v_mad_i64_i32 v[2:3], s[40:41], v4, s30, v[2:3]
	v_lshl_add_u64 v[2:3], v[2:3], 0, s[26:27]
	v_lshl_add_u64 v[18:19], v[2:3], 0, v[14:15]
	global_load_dwordx4 v[2:5], v[16:17], off
	global_load_dwordx4 v[6:9], v[18:19], off
.LBB0_12:
	s_waitcnt lgkmcnt(0)
	s_barrier
	ds_read2_b32 v[16:17], v26 offset1:65
	ds_read2_b32 v[18:19], v29 offset0:4 offset1:69
	ds_read2_b32 v[20:21], v26 offset0:130 offset1:195
	ds_read2_b32 v[22:23], v29 offset0:134 offset1:199
	s_mul_hi_i32 s23, s22, 0xea0ea0eb
	s_add_i32 s23, s23, s22
	s_lshr_b32 s22, s23, 31
	s_ashr_i32 s25, s23, 7
	s_add_i32 s25, s25, s22
	s_lshl_b32 s22, s25, 6
	s_andn2_b64 vcc, exec, s[18:19]
	s_ashr_i32 s23, s22, 31
	s_cbranch_vccnz .LBB0_9
	s_waitcnt vmcnt(3) lgkmcnt(1)
	v_pk_mul_f32 v[20:21], v[20:21], v[32:33]
	v_pk_mul_f32 v[16:17], v[16:17], v[30:31]
	s_waitcnt vmcnt(2) lgkmcnt(0)
	v_pk_mul_f32 v[22:23], v[22:23], v[36:37]
	v_pk_mul_f32 v[18:19], v[18:19], v[34:35]
	s_branch .LBB0_9
.LBB0_14:
	s_add_i32 s13, s39, 0x8c0
	s_mul_hi_u32 s18, s13, s36
	v_mov_b32_e32 v12, v179
	s_mov_b32 s3, s87
	s_mul_i32 s18, s18, s29
	s_load_dwordx2 s[20:21], s[0:1], 0xb8
	s_waitcnt lgkmcnt(0)
	s_sub_i32 s13, s13, s18
	s_lshl_b32 s12, s2, 21
	s_add_i32 s3, s3, s72
	s_sub_i32 s18, s13, s29
	s_cmp_ge_u32 s13, s29
	s_cselect_b32 s13, s18, s13
	s_sub_i32 s18, s13, s29
	s_cmp_ge_u32 s13, s29
	s_cselect_b32 s13, s18, s13
	s_sub_i32 s3, s3, s13
	s_ashr_i32 s22, s3, 31
	s_abs_i32 s3, s3
	s_mul_hi_u32 s13, s3, s36
	s_mul_i32 s13, s13, s29
	s_sub_i32 s3, s3, s13
	s_sub_i32 s13, s3, s29
	s_cmp_ge_u32 s3, s29
	s_cselect_b32 s3, s13, s3
	s_sub_i32 s13, s3, s29
	s_cmp_ge_u32 s3, s29
	s_cselect_b32 s3, s13, s3
	s_xor_b32 s23, s3, s22
	s_sub_i32 s3, s23, s22
	s_cmpk_lt_i32 s3, 0x80
	s_mov_b32 s13, s5
	s_cbranch_scc0 .LBB0_21
	s_add_u32 s18, s10, 0x1180000
	s_addc_u32 s19, s11, 0
	s_lshl_b64 s[24:25], s[12:13], 2
	s_add_u32 s20, s20, s24
	s_addc_u32 s21, s21, s25
	s_ashr_i32 s24, s3, 31
	s_lshr_b32 s24, s24, 28
	s_add_i32 s24, s3, s24
	v_ashrrev_i32_e32 v1, 4, v12
	s_waitcnt vmcnt(2)
	v_lshlrev_b32_e32 v2, 2, v12
	s_ashr_i32 s25, s24, 4
	v_and_b32_e32 v20, 60, v2
	v_lshl_add_u32 v2, s25, 6, v1
	s_lshl_b32 s24, s25, 10
	s_lshl_b32 s26, s3, 6
	v_ashrrev_i32_e32 v3, 31, v2
	s_sub_i32 s24, s26, s24
	v_lshlrev_b64 v[2:3], 12, v[2:3]
	v_lshl_add_u64 v[2:3], s[20:21], 0, v[2:3]
	s_ashr_i32 s25, s24, 31
	v_lshl_add_u64 v[2:3], s[24:25], 2, v[2:3]
	v_lshlrev_b32_e32 v10, 2, v20
	v_lshl_add_u64 v[14:15], v[2:3], 0, v[10:11]
	v_add_co_u32_e32 v16, vcc, s33, v14
	s_lshl_b32 s23, s23, 6
	s_nop 0
	v_addc_co_u32_e32 v17, vcc, 0, v15, vcc
	global_load_dwordx4 v[2:5], v[14:15], off
	global_load_dwordx4 v[6:9], v[16:17], off
	global_load_dword v52, v[14:15], off
	v_ashrrev_i32_e32 v14, 3, v12
	v_lshlrev_b32_e32 v12, 3, v12
	v_and_b32_e32 v22, 56, v12
	v_mul_lo_u32 v12, v1, s31
	v_add3_u32 v15, 0, v10, v12
	v_add3_u32 v16, 0, v12, v10
	v_mul_u32_u24_e32 v12, 0x41, v22
	v_lshlrev_b32_e32 v10, 2, v14
	v_lshlrev_b32_e32 v12, 2, v12
	s_lshl_b32 s22, s22, 6
	v_add3_u32 v17, 0, v10, v12
	v_add3_u32 v18, 0, v12, v10
	s_sub_i32 s26, s23, s22
	v_lshlrev_b32_e32 v12, 2, v20
	v_lshlrev_b32_e32 v10, 1, v22
	s_branch .LBB0_17

; __device__ __forceinline__ void tconv(const float* __restrict__ src, bf16_t* __restrict__ dst, int K, int N, const float* __restrict__ scale, float* tile, int& rot) {
;     ...
;         __syncthreads();
; #pragma unroll
;         for (int j = 0; j < 4; ++j) { tile[lr * 65 + lc + j] = v0[j]; tile[(lr + 32) * 65 + lc + j] = v1[j]; }
;         const int t2 = t + G;
;         if (t2 < nt) { const int kt2 = t2 / tn, k2 = kt2 << 6, n2 = (t2 - kt2 * tn) << 6; v0 = *(const f32x4*)(src + (size_t)(k2 + lr) * N + n2 + lc); v1 = *(const f32x4*)(src + (size_t)(k2 + lr + 32) * N + n2 + lc); }
.LBB0_17:
	s_add_i32 s27, s3, s72
	v_add_u32_e32 v13, 0x2080, v16
	s_cmpk_gt_i32 s27, 0x7f
	s_barrier
	s_waitcnt vmcnt(2)
	ds_write2_b32 v15, v2, v3 offset1:1
	s_waitcnt vmcnt(1)
	ds_write2_b32 v13, v6, v7 offset1:1
	ds_write2_b32 v15, v4, v5 offset0:2 offset1:3
	v_add_u32_e32 v13, 0x2088, v16
	s_cselect_b64 s[22:23], -1, 0
	s_cmpk_lt_i32 s27, 0x80
	s_mov_b64 s[24:25], -1
	ds_write2_b32 v13, v8, v9 offset1:1
	s_cbranch_scc1 .LBB0_19
	s_add_i32 s40, s26, s74
	s_mov_b64 s[24:25], 0

; __device__ __forceinline__ int tid_v() { int t = threadIdx.x; asm volatile("" : "+v"(t)); return t; }
; __device__ __forceinline__ int bid_s() { int b = blockIdx.x; asm volatile("" : "+s"(b)); return b; }
; __device__ __forceinline__ void tconv(const float* __restrict__ src, bf16_t* __restrict__ dst, int K, int N, const float* __restrict__ scale, float* tile, int& rot) {
;     const int tk = K >> 6, tn = N >> 6, nt = tk * tn, G = gridDim.x;
;     const int tid = tid_v(), lr = tid >> 4, lc = (tid & 15) * 4;
;     const int sn = tid >> 3, sk = (tid & 7) * 8;
;     int t = (int)((bid_s() + G - (rot % G)) % G);
;     f32x4 v0, v1;
;     if (t < nt) { const int kt = t / tn, k0 = kt << 6, n0 = (t - kt * tn) << 6; v0 = *(const f32x4*)(src + (size_t)(k0 + lr) * N + n0 + lc); v1 = *(const f32x4*)(src + (size_t)(k0 + lr + 32) * N + n0 + lc); }
; __device__ __forceinline__ void phase0(unsigned char* shm) {
;     ...
;         for (int k = 0; k < 4; ++k) tconv(IN(23) + (size_t)(l * 4 + k) * 512 * 1024, W + oWb + (size_t)k * 1024 * 512, 512, 1024, nullptr, tile, rot);
.LBB0_21:
	s_add_i32 s20, s39, 0x940
	s_mul_hi_u32 s21, s20, s36
	v_mov_b32_e32 v12, v179
	s_mov_b32 s3, s87
	s_mul_i32 s21, s21, s29
	s_load_dwordx2 s[18:19], s[0:1], 0xb8
	s_waitcnt lgkmcnt(0)
	s_sub_i32 s20, s20, s21
	s_add_i32 s3, s3, s72
	s_sub_i32 s21, s20, s29
	s_cmp_ge_u32 s20, s29
	s_cselect_b32 s20, s21, s20
	s_sub_i32 s21, s20, s29
	s_cmp_ge_u32 s20, s29
	s_cselect_b32 s20, s21, s20
	s_sub_i32 s3, s3, s20
	s_ashr_i32 s22, s3, 31
	s_abs_i32 s3, s3
	s_mul_hi_u32 s20, s3, s36
	s_mul_i32 s20, s20, s29
	s_sub_i32 s3, s3, s20
	s_sub_i32 s20, s3, s29
	s_cmp_ge_u32 s3, s29
	s_cselect_b32 s3, s20, s3
	s_sub_i32 s20, s3, s29
	s_cmp_ge_u32 s3, s29
	s_cselect_b32 s3, s20, s3
	s_xor_b32 s23, s3, s22
	s_sub_i32 s3, s23, s22
	s_cmpk_gt_i32 s3, 0x7f
	s_cbranch_scc1 .LBB0_28
	s_lshl_b64 s[20:21], s[12:13], 2
	s_add_u32 s18, s18, s20
	s_addc_u32 s19, s19, s21
	s_add_u32 s18, s18, 0x200000
	s_addc_u32 s19, s19, 0
	s_add_u32 s20, s10, 0x1280000
	s_addc_u32 s21, s11, 0
	s_ashr_i32 s24, s3, 31
	s_lshr_b32 s24, s24, 28
	s_add_i32 s24, s3, s24
	v_ashrrev_i32_e32 v1, 4, v12
	s_waitcnt vmcnt(2)
	v_lshlrev_b32_e32 v2, 2, v12
	s_ashr_i32 s25, s24, 4
	v_and_b32_e32 v20, 60, v2
	v_lshl_add_u32 v2, s25, 6, v1
	s_lshl_b32 s24, s25, 10
	s_lshl_b32 s26, s3, 6
	v_ashrrev_i32_e32 v3, 31, v2
	s_sub_i32 s24, s26, s24
	v_lshlrev_b64 v[2:3], 12, v[2:3]
	v_lshl_add_u64 v[2:3], s[18:19], 0, v[2:3]
	s_ashr_i32 s25, s24, 31
	v_lshl_add_u64 v[2:3], s[24:25], 2, v[2:3]
	v_lshlrev_b32_e32 v10, 2, v20
	v_lshl_add_u64 v[14:15], v[2:3], 0, v[10:11]
	v_add_co_u32_e32 v16, vcc, s33, v14
	s_lshl_b32 s23, s23, 6
	s_nop 0
	v_addc_co_u32_e32 v17, vcc, 0, v15, vcc
	global_load_dwordx4 v[2:5], v[14:15], off
	global_load_dwordx4 v[6:9], v[16:17], off
	global_load_dword v52, v[14:15], off
	v_ashrrev_i32_e32 v14, 3, v12
	v_lshlrev_b32_e32 v12, 3, v12
	v_and_b32_e32 v22, 56, v12
	v_mul_lo_u32 v12, v1, s31
	v_add3_u32 v15, 0, v10, v12
	v_add3_u32 v16, 0, v12, v10
	v_mul_u32_u24_e32 v12, 0x41, v22
	v_lshlrev_b32_e32 v10, 2, v14
	v_lshlrev_b32_e32 v12, 2, v12
	s_lshl_b32 s22, s22, 6
	v_add3_u32 v17, 0, v10, v12
	v_add3_u32 v18, 0, v12, v10
	s_sub_i32 s26, s23, s22
	v_lshlrev_b32_e32 v12, 2, v20
	v_lshlrev_b32_e32 v10, 1, v22
	s_branch .LBB0_24

; __device__ __forceinline__ int tid_v() { int t = threadIdx.x; asm volatile("" : "+v"(t)); return t; }
; __device__ __forceinline__ int bid_s() { int b = blockIdx.x; asm volatile("" : "+s"(b)); return b; }
; __device__ __forceinline__ void tconv(const float* __restrict__ src, bf16_t* __restrict__ dst, int K, int N, const float* __restrict__ scale, float* tile, int& rot) {
;     const int tk = K >> 6, tn = N >> 6, nt = tk * tn, G = gridDim.x;
;     const int tid = tid_v(), lr = tid >> 4, lc = (tid & 15) * 4;
;     const int sn = tid >> 3, sk = (tid & 7) * 8;
;     int t = (int)((bid_s() + G - (rot % G)) % G);
;     f32x4 v0, v1;
;     if (t < nt) { const int kt = t / tn, k0 = kt << 6, n0 = (t - kt * tn) << 6; v0 = *(const f32x4*)(src + (size_t)(k0 + lr) * N + n0 + lc); v1 = *(const f32x4*)(src + (size_t)(k0 + lr + 32) * N + n0 + lc); }
; __device__ __forceinline__ void phase0(unsigned char* shm) {
;     ...
;         for (int k = 0; k < 4; ++k) tconv(IN(23) + (size_t)(l * 4 + k) * 512 * 1024, W + oWb + (size_t)k * 1024 * 512, 512, 1024, nullptr, tile, rot);
.LBB0_28:
	s_add_i32 s20, s39, 0x9c0
	s_mul_hi_u32 s21, s20, s36
	v_mov_b32_e32 v12, v179
	s_mov_b32 s3, s87
	s_mul_i32 s21, s21, s29
	s_load_dwordx2 s[18:19], s[0:1], 0xb8
	s_waitcnt lgkmcnt(0)
	s_sub_i32 s20, s20, s21
	s_add_i32 s3, s3, s72
	s_sub_i32 s21, s20, s29
	s_cmp_ge_u32 s20, s29
	s_cselect_b32 s20, s21, s20
	s_sub_i32 s21, s20, s29
	s_cmp_ge_u32 s20, s29
	s_cselect_b32 s20, s21, s20
	s_sub_i32 s3, s3, s20
	s_ashr_i32 s22, s3, 31
	s_abs_i32 s3, s3
	s_mul_hi_u32 s20, s3, s36
	s_mul_i32 s20, s20, s29
	s_sub_i32 s3, s3, s20
	s_sub_i32 s20, s3, s29
	s_cmp_ge_u32 s3, s29
	s_cselect_b32 s3, s20, s3
	s_sub_i32 s20, s3, s29
	s_cmp_ge_u32 s3, s29
	s_cselect_b32 s3, s20, s3
	s_xor_b32 s23, s3, s22
	s_sub_i32 s3, s23, s22
	s_cmpk_gt_i32 s3, 0x7f
	s_cbranch_scc1 .LBB0_35
	s_lshl_b64 s[20:21], s[12:13], 2
	s_add_u32 s18, s18, s20
	s_addc_u32 s19, s19, s21
	s_add_u32 s18, s18, 0x400000
	s_addc_u32 s19, s19, 0
	s_add_u32 s20, s10, 0x1380000
	s_addc_u32 s21, s11, 0
	s_ashr_i32 s24, s3, 31
	s_lshr_b32 s24, s24, 28
	s_add_i32 s24, s3, s24
	v_ashrrev_i32_e32 v1, 4, v12
	s_waitcnt vmcnt(2)
	v_lshlrev_b32_e32 v2, 2, v12
	s_ashr_i32 s25, s24, 4
	v_and_b32_e32 v20, 60, v2
	v_lshl_add_u32 v2, s25, 6, v1
	s_lshl_b32 s24, s25, 10
	s_lshl_b32 s26, s3, 6
	v_ashrrev_i32_e32 v3, 31, v2
	s_sub_i32 s24, s26, s24
	v_lshlrev_b64 v[2:3], 12, v[2:3]
	v_lshl_add_u64 v[2:3], s[18:19], 0, v[2:3]
	s_ashr_i32 s25, s24, 31
	v_lshl_add_u64 v[2:3], s[24:25], 2, v[2:3]
	v_lshlrev_b32_e32 v10, 2, v20
	v_lshl_add_u64 v[14:15], v[2:3], 0, v[10:11]
	v_add_co_u32_e32 v16, vcc, s33, v14
	s_lshl_b32 s23, s23, 6
	s_nop 0
	v_addc_co_u32_e32 v17, vcc, 0, v15, vcc
	global_load_dwordx4 v[2:5], v[14:15], off
	global_load_dwordx4 v[6:9], v[16:17], off
	global_load_dword v52, v[14:15], off
	v_ashrrev_i32_e32 v14, 3, v12
	v_lshlrev_b32_e32 v12, 3, v12
	v_and_b32_e32 v22, 56, v12
	v_mul_lo_u32 v12, v1, s31
	v_add3_u32 v15, 0, v10, v12
	v_add3_u32 v16, 0, v12, v10
	v_mul_u32_u24_e32 v12, 0x41, v22
	v_lshlrev_b32_e32 v10, 2, v14
	v_lshlrev_b32_e32 v12, 2, v12
	s_lshl_b32 s22, s22, 6
	v_add3_u32 v17, 0, v10, v12
	v_add3_u32 v18, 0, v12, v10
	s_sub_i32 s26, s23, s22
	v_lshlrev_b32_e32 v12, 2, v20
	v_lshlrev_b32_e32 v10, 1, v22
	s_branch .LBB0_31

; __device__ __forceinline__ int tid_v() { int t = threadIdx.x; asm volatile("" : "+v"(t)); return t; }
; __device__ __forceinline__ int bid_s() { int b = blockIdx.x; asm volatile("" : "+s"(b)); return b; }
; __device__ __forceinline__ void tconv(const float* __restrict__ src, bf16_t* __restrict__ dst, int K, int N, const float* __restrict__ scale, float* tile, int& rot) {
;     const int tk = K >> 6, tn = N >> 6, nt = tk * tn, G = gridDim.x;
;     const int tid = tid_v(), lr = tid >> 4, lc = (tid & 15) * 4;
;     const int sn = tid >> 3, sk = (tid & 7) * 8;
;     int t = (int)((bid_s() + G - (rot % G)) % G);
;     f32x4 v0, v1;
;     if (t < nt) { const int kt = t / tn, k0 = kt << 6, n0 = (t - kt * tn) << 6; v0 = *(const f32x4*)(src + (size_t)(k0 + lr) * N + n0 + lc); v1 = *(const f32x4*)(src + (size_t)(k0 + lr + 32) * N + n0 + lc); }
; __device__ __forceinline__ void phase0(unsigned char* shm) {
;     ...
;         for (int k = 0; k < 4; ++k) tconv(IN(23) + (size_t)(l * 4 + k) * 512 * 1024, W + oWb + (size_t)k * 1024 * 512, 512, 1024, nullptr, tile, rot);
.LBB0_35:
	s_add_i32 s20, s39, 0xa40
	s_mul_hi_u32 s21, s20, s36
	v_mov_b32_e32 v12, v179
	s_mov_b32 s3, s87
	s_mul_i32 s21, s21, s29
	s_load_dwordx2 s[18:19], s[0:1], 0xb8
	s_waitcnt lgkmcnt(0)
	s_sub_i32 s20, s20, s21
	s_add_i32 s3, s3, s72
	s_sub_i32 s21, s20, s29
	s_cmp_ge_u32 s20, s29
	s_cselect_b32 s20, s21, s20
	s_sub_i32 s21, s20, s29
	s_cmp_ge_u32 s20, s29
	s_cselect_b32 s20, s21, s20
	s_sub_i32 s3, s3, s20
	s_ashr_i32 s20, s3, 31
	s_abs_i32 s3, s3
	s_mul_hi_u32 s21, s3, s36
	s_mul_i32 s21, s21, s29
	s_sub_i32 s3, s3, s21
	s_sub_i32 s21, s3, s29
	s_cmp_ge_u32 s3, s29
	s_cselect_b32 s3, s21, s3
	s_sub_i32 s21, s3, s29
	s_cmp_ge_u32 s3, s29
	s_cselect_b32 s3, s21, s3
	s_xor_b32 s21, s3, s20
	s_sub_i32 s3, s21, s20
	s_cmpk_gt_i32 s3, 0x7f
	s_cbranch_scc1 .LBB0_42
	s_lshl_b64 s[12:13], s[12:13], 2
	s_add_u32 s12, s18, s12
	s_addc_u32 s13, s19, s13
	s_add_u32 s12, s12, 0x600000
	s_addc_u32 s13, s13, 0
	s_add_u32 s18, s10, 0x1480000
	s_addc_u32 s19, s11, 0
	s_ashr_i32 s22, s3, 31
	s_lshr_b32 s22, s22, 28
	s_add_i32 s22, s3, s22
	v_ashrrev_i32_e32 v1, 4, v12
	s_waitcnt vmcnt(2)
	v_lshlrev_b32_e32 v2, 2, v12
	s_ashr_i32 s23, s22, 4
	v_and_b32_e32 v20, 60, v2
	v_lshl_add_u32 v2, s23, 6, v1
	s_lshl_b32 s22, s23, 10
	s_lshl_b32 s24, s3, 6
	v_ashrrev_i32_e32 v3, 31, v2
	s_sub_i32 s22, s24, s22
	v_lshlrev_b64 v[2:3], 12, v[2:3]
	v_lshl_add_u64 v[2:3], s[12:13], 0, v[2:3]
	s_ashr_i32 s23, s22, 31
	v_lshl_add_u64 v[2:3], s[22:23], 2, v[2:3]
	v_lshlrev_b32_e32 v10, 2, v20
	v_lshl_add_u64 v[14:15], v[2:3], 0, v[10:11]
	v_add_co_u32_e32 v16, vcc, s33, v14
	s_lshl_b32 s21, s21, 6
	s_nop 0
	v_addc_co_u32_e32 v17, vcc, 0, v15, vcc
	global_load_dwordx4 v[2:5], v[14:15], off
	global_load_dwordx4 v[6:9], v[16:17], off
	global_load_dword v52, v[14:15], off
	v_ashrrev_i32_e32 v14, 3, v12
	v_lshlrev_b32_e32 v12, 3, v12
	v_and_b32_e32 v22, 56, v12
	v_mul_lo_u32 v12, v1, s31
	v_add3_u32 v15, 0, v10, v12
	v_add3_u32 v16, 0, v12, v10
	v_mul_u32_u24_e32 v12, 0x41, v22
	v_lshlrev_b32_e32 v10, 2, v14
	v_lshlrev_b32_e32 v12, 2, v12
	s_lshl_b32 s20, s20, 6
	v_add3_u32 v17, 0, v10, v12
	v_add3_u32 v18, 0, v12, v10
	s_sub_i32 s24, s21, s20
	v_lshlrev_b32_e32 v12, 2, v20
	v_lshlrev_b32_e32 v10, 1, v22
	s_branch .LBB0_38

; __device__ __forceinline__ void tconv(const float* __restrict__ src, bf16_t* __restrict__ dst, int K, int N, const float* __restrict__ scale, float* tile, int& rot) {
;     ...
;         __syncthreads();
; #pragma unroll
;         for (int j = 0; j < 4; ++j) { tile[lr * 65 + lc + j] = v0[j]; tile[(lr + 32) * 65 + lc + j] = v1[j]; }
;         const int t2 = t + G;
;         if (t2 < nt) { const int kt2 = t2 / tn, k2 = kt2 << 6, n2 = (t2 - kt2 * tn) << 6; v0 = *(const f32x4*)(src + (size_t)(k2 + lr) * N + n2 + lc); v1 = *(const f32x4*)(src + (size_t)(k2 + lr + 32) * N + n2 + lc); }
.LBB0_38:
	s_add_i32 s25, s3, s72
	v_add_u32_e32 v13, 0x2080, v16
	s_cmpk_gt_i32 s25, 0x7f
	s_barrier
	s_waitcnt vmcnt(2)
	ds_write2_b32 v15, v2, v3 offset1:1
	s_waitcnt vmcnt(1)
	ds_write2_b32 v13, v6, v7 offset1:1
	ds_write2_b32 v15, v4, v5 offset0:2 offset1:3
	v_add_u32_e32 v13, 0x2088, v16
	s_cselect_b64 s[20:21], -1, 0
	s_cmpk_lt_i32 s25, 0x80
	s_mov_b64 s[22:23], -1
	ds_write2_b32 v13, v8, v9 offset1:1
	s_cbranch_scc1 .LBB0_40
	s_add_i32 s26, s24, s74
	s_mov_b64 s[22:23], 0

; __device__ __forceinline__ int tid_v() { int t = threadIdx.x; asm volatile("" : "+v"(t)); return t; }
; __device__ __forceinline__ int bid_s() { int b = blockIdx.x; asm volatile("" : "+s"(b)); return b; }
; __device__ __forceinline__ void tconv(const float* __restrict__ src, bf16_t* __restrict__ dst, int K, int N, const float* __restrict__ scale, float* tile, int& rot) {
;     const int tk = K >> 6, tn = N >> 6, nt = tk * tn, G = gridDim.x;
;     const int tid = tid_v(), lr = tid >> 4, lc = (tid & 15) * 4;
;     const int sn = tid >> 3, sk = (tid & 7) * 8;
;     int t = (int)((bid_s() + G - (rot % G)) % G);
;     f32x4 v0, v1;
;     if (t < nt) { const int kt = t / tn, k0 = kt << 6, n0 = (t - kt * tn) << 6; v0 = *(const f32x4*)(src + (size_t)(k0 + lr) * N + n0 + lc); v1 = *(const f32x4*)(src + (size_t)(k0 + lr + 32) * N + n0 + lc); }
; __device__ __forceinline__ void phase0(unsigned char* shm) {
;     ...
;         tconv(IN(24) + (size_t)l * 1024 * 1024, W + oWo, 1024, 1024, nullptr, tile, rot);
.LBB0_42:
	s_add_i32 s21, s39, 0xac0
	s_mul_hi_u32 s22, s21, s36
	v_mov_b32_e32 v12, v179
	s_mov_b32 s20, s87
	s_mul_i32 s22, s22, s29
	s_mov_b32 s3, s5
	s_load_dwordx2 s[18:19], s[0:1], 0xc0
	s_waitcnt lgkmcnt(0)
	s_sub_i32 s21, s21, s22
	s_lshl_b64 s[12:13], s[2:3], 20
	s_add_i32 s20, s20, s72
	s_sub_i32 s22, s21, s29
	s_cmp_ge_u32 s21, s29
	s_cselect_b32 s21, s22, s21
	s_sub_i32 s22, s21, s29
	s_cmp_ge_u32 s21, s29
	s_cselect_b32 s21, s22, s21
	s_sub_i32 s20, s20, s21
	s_ashr_i32 s22, s20, 31
	s_abs_i32 s20, s20
	s_mul_hi_u32 s21, s20, s36
	s_mul_i32 s21, s21, s29
	s_sub_i32 s20, s20, s21
	s_sub_i32 s21, s20, s29
	s_cmp_ge_u32 s20, s29
	s_cselect_b32 s20, s21, s20
	s_sub_i32 s21, s20, s29
	s_cmp_ge_u32 s20, s29
	s_cselect_b32 s20, s21, s20
	s_xor_b32 s23, s20, s22
	s_sub_i32 s26, s23, s22
	s_cmpk_lt_i32 s26, 0x100
	s_cbranch_scc0 .LBB0_49
	s_lshl_b64 s[20:21], s[12:13], 2
	s_add_u32 s18, s18, s20
	s_addc_u32 s19, s19, s21
	s_add_u32 s20, s10, 0x1580000
	s_addc_u32 s21, s11, 0
	s_ashr_i32 s24, s26, 31
	s_lshr_b32 s24, s24, 28
	s_add_i32 s24, s26, s24
	v_ashrrev_i32_e32 v1, 4, v12
	s_waitcnt vmcnt(2)
	v_lshlrev_b32_e32 v2, 2, v12
	s_ashr_i32 s25, s24, 4
	v_and_b32_e32 v20, 60, v2
	v_lshl_add_u32 v2, s25, 6, v1
	s_lshl_b32 s24, s25, 10
	s_lshl_b32 s27, s26, 6
	v_ashrrev_i32_e32 v3, 31, v2
	s_sub_i32 s24, s27, s24
	v_lshlrev_b64 v[2:3], 12, v[2:3]
	v_lshl_add_u64 v[2:3], s[18:19], 0, v[2:3]
	s_ashr_i32 s25, s24, 31
	v_lshl_add_u64 v[2:3], s[24:25], 2, v[2:3]
	v_lshlrev_b32_e32 v10, 2, v20
	v_lshl_add_u64 v[14:15], v[2:3], 0, v[10:11]
	v_add_co_u32_e32 v16, vcc, s33, v14
	s_lshl_b32 s23, s23, 6
	s_nop 0
	v_addc_co_u32_e32 v17, vcc, 0, v15, vcc
	global_load_dwordx4 v[2:5], v[14:15], off
	global_load_dwordx4 v[6:9], v[16:17], off
	global_load_dword v52, v[14:15], off
	v_ashrrev_i32_e32 v14, 3, v12
	v_lshlrev_b32_e32 v12, 3, v12
	v_and_b32_e32 v22, 56, v12
	v_mul_lo_u32 v12, v1, s31
	v_add3_u32 v15, 0, v10, v12
	v_add3_u32 v16, 0, v12, v10
	v_mul_u32_u24_e32 v12, 0x41, v22
	v_lshlrev_b32_e32 v10, 2, v14
	v_lshlrev_b32_e32 v12, 2, v12
	s_lshl_b32 s22, s22, 6
	v_add3_u32 v17, 0, v10, v12
	v_add3_u32 v18, 0, v12, v10
	s_sub_i32 s27, s23, s22
	v_lshlrev_b32_e32 v12, 2, v20
	v_lshlrev_b32_e32 v10, 1, v22
	s_branch .LBB0_45

; __device__ __forceinline__ void tconv(const float* __restrict__ src, bf16_t* __restrict__ dst, int K, int N, const float* __restrict__ scale, float* tile, int& rot) {
;     ...
;         __syncthreads();
; #pragma unroll
;         for (int j = 0; j < 4; ++j) { tile[lr * 65 + lc + j] = v0[j]; tile[(lr + 32) * 65 + lc + j] = v1[j]; }
;         const int t2 = t + G;
;         if (t2 < nt) { const int kt2 = t2 / tn, k2 = kt2 << 6, n2 = (t2 - kt2 * tn) << 6; v0 = *(const f32x4*)(src + (size_t)(k2 + lr) * N + n2 + lc); v1 = *(const f32x4*)(src + (size_t)(k2 + lr + 32) * N + n2 + lc); }
.LBB0_45:
	s_add_i32 s40, s26, s72
	v_add_u32_e32 v13, 0x2080, v16
	s_cmpk_gt_i32 s40, 0xff
	s_barrier
	s_waitcnt vmcnt(2)
	ds_write2_b32 v15, v2, v3 offset1:1
	s_waitcnt vmcnt(1)
	ds_write2_b32 v13, v6, v7 offset1:1
	ds_write2_b32 v15, v4, v5 offset0:2 offset1:3
	v_add_u32_e32 v13, 0x2088, v16
	s_cselect_b64 s[22:23], -1, 0
	s_cmpk_lt_i32 s40, 0x100
	s_mov_b64 s[24:25], -1
	ds_write2_b32 v13, v8, v9 offset1:1
	s_cbranch_scc1 .LBB0_47
	s_add_i32 s41, s27, s74
	s_mov_b64 s[24:25], 0

; __device__ __forceinline__ int tid_v() { int t = threadIdx.x; asm volatile("" : "+v"(t)); return t; }
; __device__ __forceinline__ int bid_s() { int b = blockIdx.x; asm volatile("" : "+s"(b)); return b; }
; __device__ __forceinline__ void tconv(const float* __restrict__ src, bf16_t* __restrict__ dst, int K, int N, const float* __restrict__ scale, float* tile, int& rot) {
;     const int tk = K >> 6, tn = N >> 6, nt = tk * tn, G = gridDim.x;
;     const int tid = tid_v(), lr = tid >> 4, lc = (tid & 15) * 4;
;     const int sn = tid >> 3, sk = (tid & 7) * 8;
;     int t = (int)((bid_s() + G - (rot % G)) % G);
;     f32x4 v0, v1;
;     if (t < nt) { const int kt = t / tn, k0 = kt << 6, n0 = (t - kt * tn) << 6; v0 = *(const f32x4*)(src + (size_t)(k0 + lr) * N + n0 + lc); v1 = *(const f32x4*)(src + (size_t)(k0 + lr + 32) * N + n0 + lc); }
; __device__ __forceinline__ void phase0(unsigned char* shm) {
;     ...
;         tconv(IN(26) + (size_t)l * 1024 * 5632, W + oWup, 1024, 5632, IN(25) + l * 1024, tile, rot);
.LBB0_49:
	s_add_i32 s21, s39, 0xbc0
	s_mul_hi_u32 s24, s21, s36
	s_load_dwordx2 s[18:19], s[0:1], 0xd0
	s_waitcnt lgkmcnt(0)
	v_mov_b32_e32 v12, v179
	s_mov_b32 s20, s87
	s_mul_i32 s24, s24, s29
	s_load_dwordx2 s[22:23], s[0:1], 0xc8
	s_waitcnt lgkmcnt(0)
	s_sub_i32 s21, s21, s24
	s_add_i32 s20, s20, s72
	s_sub_i32 s24, s21, s29
	s_cmp_ge_u32 s21, s29
	s_cselect_b32 s21, s24, s21
	s_sub_i32 s24, s21, s29
	s_cmp_ge_u32 s21, s29
	s_cselect_b32 s21, s24, s21
	s_sub_i32 s20, s20, s21
	s_ashr_i32 s24, s20, 31
	s_abs_i32 s20, s20
	s_mul_hi_u32 s21, s20, s36
	s_mul_i32 s21, s21, s29
	s_sub_i32 s20, s20, s21
	s_sub_i32 s21, s20, s29
	s_cmp_ge_u32 s20, s29
	s_cselect_b32 s20, s21, s20
	s_sub_i32 s21, s20, s29
	s_cmp_ge_u32 s20, s29
	s_cselect_b32 s20, s21, s20
	s_xor_b32 s25, s20, s24
	s_sub_i32 s26, s25, s24
	s_cmpk_gt_i32 s26, 0x57f
	s_cbranch_scc1 .LBB0_56
	s_mul_i32 s20, s2, 0x1600000
	s_add_u32 s18, s18, s20
	s_addc_u32 s19, s19, 0
	s_add_u32 s20, s10, 0x1780000
	s_addc_u32 s21, s11, 0
	s_lshl_b64 s[40:41], s[4:5], 2
	s_add_u32 s40, s22, s40
	s_mul_hi_i32 s27, s26, 0x2e8ba2e9
	s_addc_u32 s41, s23, s41
	s_lshr_b32 s42, s27, 31
	s_ashr_i32 s27, s27, 4
	s_add_i32 s27, s27, s42
	s_mul_i32 s42, s27, 0x3ffffa8
	s_add_i32 s42, s42, s26
	v_ashrrev_i32_e32 v1, 4, v12
	s_waitcnt vmcnt(2)
	v_lshlrev_b32_e32 v2, 2, v12
	s_lshl_b32 s42, s42, 6
	v_and_b32_e32 v14, 60, v2
	s_waitcnt vmcnt(1)
	v_lshl_add_u32 v6, s27, 6, v1
	v_mov_b64_e32 v[2:3], s[18:19]
	s_ashr_i32 s43, s42, 31
	v_mad_i64_i32 v[4:5], s[44:45], v6, s34, v[2:3]
	s_lshl_b64 s[42:43], s[42:43], 2
	v_lshl_add_u64 v[4:5], v[4:5], 0, s[42:43]
	v_lshlrev_b32_e32 v10, 2, v14
	v_lshl_add_u64 v[16:17], v[4:5], 0, v[10:11]
	v_add_u32_e32 v4, 32, v6
	v_mad_i64_i32 v[2:3], s[44:45], v4, s34, v[2:3]
	v_lshl_add_u64 v[2:3], v[2:3], 0, s[42:43]
	v_lshl_add_u64 v[18:19], v[2:3], 0, v[10:11]
	global_load_dwordx4 v[2:5], v[16:17], off
	global_load_dwordx4 v[6:9], v[18:19], off
	global_load_dword v52, v[16:17], off
	v_ashrrev_i32_e32 v24, 3, v12
	v_lshlrev_b32_e32 v12, 3, v12
	v_and_b32_e32 v16, 56, v12
	v_mul_lo_u32 v12, v1, s31
	v_add3_u32 v25, 0, v10, v12
	v_add3_u32 v26, 0, v12, v10
	v_lshlrev_b32_e32 v10, 2, v16
	s_cmp_lg_u64 s[22:23], 0
	v_lshl_add_u64 v[12:13], s[40:41], 0, v[10:11]
	v_mul_u32_u24_e32 v10, 0x41, v16
	v_lshlrev_b32_e32 v15, 2, v24
	s_cselect_b64 s[22:23], -1, 0
	v_lshlrev_b32_e32 v10, 2, v10
	s_lshl_b32 s25, s25, 6
	s_lshl_b32 s24, s24, 6
	v_add3_u32 v27, 0, v15, v10
	v_add3_u32 v28, 0, v10, v15
	s_sub_i32 s40, s25, s24
	v_lshlrev_b32_e32 v14, 2, v14
	v_lshlrev_b32_e32 v10, 1, v16
	s_branch .LBB0_52

; __device__ __forceinline__ u32x4 pack8(const f32x4& v0, const f32x4& v1) { u32x4 w; w.x = cvt_pk_bf16(v0[0], v0[1]); w.y = cvt_pk_bf16(v0[2], v0[3]); w.z = cvt_pk_bf16(v1[0], v1[1]); w.w = cvt_pk_bf16(v1[2], v1[3]); return w; }
; __device__ __forceinline__ void tconv(const float* __restrict__ src, bf16_t* __restrict__ dst, int K, int N, const float* __restrict__ scale, float* tile, int& rot) {
;     ...
;     for (; t < nt; t += G) {
;         const int kt = t / tn, k0 = kt << 6, n0 = (t - kt * tn) << 6;
;         __syncthreads();
; #pragma unroll
;         for (int j = 0; j < 4; ++j) { tile[lr * 65 + lc + j] = v0[j]; tile[(lr + 32) * 65 + lc + j] = v1[j]; }
;         const int t2 = t + G;
;         if (t2 < nt) { const int kt2 = t2 / tn, k2 = kt2 << 6, n2 = (t2 - kt2 * tn) << 6; v0 = *(const f32x4*)(src + (size_t)(k2 + lr) * N + n2 + lc); v1 = *(const f32x4*)(src + (size_t)(k2 + lr + 32) * N + n2 + lc); }
;         __syncthreads();
;         f32x4 a, bb;
; #pragma unroll
;         for (int j = 0; j < 4; ++j) { a[j] = tile[(sk + j) * 65 + sn]; bb[j] = tile[(sk + 4 + j) * 65 + sn]; }
;         if (scale) { a *= *(const f32x4*)(scale + k0 + sk); bb *= *(const f32x4*)(scale + k0 + sk + 4); }
;         *(u32x4*)(dst + (size_t)(n0 + sn) * K + k0 + sk) = pack8(a, bb);
;     }
; __device__ __forceinline__ void phase0(unsigned char* shm) {
;     ...
;         tconv(IN(29) + (size_t)l * 2816 * 1024, W + oWd, 2816, 1024, nullptr, tile, rot);
.LBB0_52:
	s_mul_hi_i32 s100, s26, 0x2e8ba2e9
	s_lshr_b32 s101, s100, 31
	s_ashr_i32 s100, s100, 4
	s_add_i32 s100, s100, s101
	s_lshl_b32 s100, s100, 6
	s_ashr_i32 s101, s100, 31
	v_lshl_add_u64 v[38:39], s[100:101], 2, v[12:13]
	global_load_dwordx4 v[30:33], v[38:39], off
	global_load_dwordx4 v[34:37], v[38:39], off offset:16
	s_add_i32 s41, s26, s72
	s_cmpk_gt_i32 s41, 0x57f
	v_add_u32_e32 v15, 0x2080, v26
	s_cselect_b64 s[24:25], -1, 0
	s_barrier
	s_waitcnt vmcnt(4)
	ds_write2_b32 v25, v2, v3 offset1:1
	s_waitcnt vmcnt(3)
	ds_write2_b32 v15, v6, v7 offset1:1
	ds_write2_b32 v25, v4, v5 offset0:2 offset1:3
	v_add_u32_e32 v15, 0x2088, v26
	s_and_b64 vcc, exec, s[24:25]
	ds_write2_b32 v15, v8, v9 offset1:1
	s_cbranch_vccnz .Ltc_drain_52
	s_mul_hi_i32 s27, s41, 0x2e8ba2e9
	s_lshr_b32 s42, s27, 31
	s_ashr_i32 s27, s27, 4
	s_add_i32 s27, s27, s42
	s_mul_i32 s42, s27, 0xffffea00
	s_add_i32 s43, s74, s40
	s_add_i32 s42, s43, s42
	v_lshl_add_u32 v6, s27, 6, v1
	v_mov_b64_e32 v[2:3], s[18:19]
	s_ashr_i32 s43, s42, 31
	v_mad_i64_i32 v[4:5], s[44:45], v6, s34, v[2:3]
	s_lshl_b64 s[42:43], s[42:43], 2
	v_lshl_add_u64 v[4:5], v[4:5], 0, s[42:43]
	v_mov_b32_e32 v15, v11
	v_lshl_add_u64 v[16:17], v[4:5], 0, v[14:15]
	v_add_u32_e32 v4, 32, v6
	v_mad_i64_i32 v[2:3], s[44:45], v4, s34, v[2:3]
	v_lshl_add_u64 v[2:3], v[2:3], 0, s[42:43]
	v_lshl_add_u64 v[18:19], v[2:3], 0, v[14:15]
	global_load_dwordx4 v[2:5], v[16:17], off
	global_load_dwordx4 v[6:9], v[18:19], off
.LBB0_54:
	v_add_u32_e32 v15, 0x400, v28
	s_waitcnt lgkmcnt(0)
	s_barrier
	ds_read2_b32 v[16:17], v27 offset1:65
	ds_read2_b32 v[18:19], v15 offset0:4 offset1:69
	ds_read2_b32 v[20:21], v27 offset0:130 offset1:195
	ds_read2_b32 v[22:23], v15 offset0:134 offset1:199
	s_mul_hi_i32 s26, s26, 0x2e8ba2e9
	s_lshr_b32 s27, s26, 31
	s_ashr_i32 s42, s26, 4
	s_add_i32 s42, s42, s27
	s_lshl_b32 s26, s42, 6
	s_andn2_b64 vcc, exec, s[22:23]
	s_ashr_i32 s27, s26, 31
	s_cbranch_vccnz .LBB0_51
	s_waitcnt vmcnt(3) lgkmcnt(1)
	v_pk_mul_f32 v[20:21], v[20:21], v[32:33]
	v_pk_mul_f32 v[16:17], v[16:17], v[30:31]
	s_waitcnt vmcnt(2) lgkmcnt(0)
	v_pk_mul_f32 v[22:23], v[22:23], v[36:37]
	v_pk_mul_f32 v[18:19], v[18:19], v[34:35]
	s_branch .LBB0_51
.LBB0_56:
	s_add_i32 s21, s39, 0x1140
	s_mul_hi_u32 s22, s21, s36
	v_mov_b32_e32 v12, v179
	s_mov_b32 s20, s87
	s_mul_i32 s22, s22, s29
	s_load_dwordx2 s[18:19], s[0:1], 0xe8
	s_waitcnt lgkmcnt(0)
	s_sub_i32 s21, s21, s22
	s_add_i32 s20, s20, s72
	s_sub_i32 s22, s21, s29
	s_cmp_ge_u32 s21, s29
	s_cselect_b32 s21, s22, s21
	s_sub_i32 s22, s21, s29
	s_cmp_ge_u32 s21, s29
	s_cselect_b32 s21, s22, s21
	s_sub_i32 s20, s20, s21
	s_ashr_i32 s22, s20, 31
	s_abs_i32 s20, s20
	s_mul_hi_u32 s21, s20, s36
	s_mul_i32 s21, s21, s29
	s_sub_i32 s20, s20, s21
	s_sub_i32 s21, s20, s29
	s_cmp_ge_u32 s20, s29
	s_cselect_b32 s20, s21, s20
	s_sub_i32 s21, s20, s29
	s_cmp_ge_u32 s20, s29
	s_cselect_b32 s20, s21, s20
	s_xor_b32 s23, s20, s22
	s_sub_i32 s26, s23, s22
	s_cmpk_gt_i32 s26, 0x2bf
	s_cbranch_scc1 .LBB0_63
	s_mul_i32 s20, s2, 0xb00000
	s_add_u32 s18, s18, s20
	s_addc_u32 s19, s19, 0
	s_add_u32 s20, s10, 0x2280000
	s_addc_u32 s21, s11, 0
	s_ashr_i32 s24, s26, 31
	s_lshr_b32 s24, s24, 28
	s_add_i32 s24, s26, s24
	v_ashrrev_i32_e32 v1, 4, v12
	s_waitcnt vmcnt(2)
	v_lshlrev_b32_e32 v2, 2, v12
	s_ashr_i32 s25, s24, 4
	v_and_b32_e32 v20, 60, v2
	v_lshl_add_u32 v2, s25, 6, v1
	s_lshl_b32 s24, s25, 10
	s_lshl_b32 s27, s26, 6
	v_ashrrev_i32_e32 v3, 31, v2
	s_sub_i32 s24, s27, s24
	v_lshlrev_b64 v[2:3], 12, v[2:3]
	v_lshl_add_u64 v[2:3], s[18:19], 0, v[2:3]
	s_ashr_i32 s25, s24, 31
	v_lshl_add_u64 v[2:3], s[24:25], 2, v[2:3]
	v_lshlrev_b32_e32 v10, 2, v20
	v_lshl_add_u64 v[14:15], v[2:3], 0, v[10:11]
	v_add_co_u32_e32 v16, vcc, s33, v14
	s_lshl_b32 s23, s23, 6
	s_nop 0
	v_addc_co_u32_e32 v17, vcc, 0, v15, vcc
	global_load_dwordx4 v[2:5], v[14:15], off
	global_load_dwordx4 v[6:9], v[16:17], off
	global_load_dword v52, v[14:15], off
	v_ashrrev_i32_e32 v14, 3, v12
	v_lshlrev_b32_e32 v12, 3, v12
	v_and_b32_e32 v22, 56, v12
	v_mul_lo_u32 v12, v1, s31
	v_add3_u32 v15, 0, v10, v12
	v_add3_u32 v16, 0, v12, v10
	v_mul_u32_u24_e32 v12, 0x41, v22
	v_lshlrev_b32_e32 v10, 2, v14
	v_lshlrev_b32_e32 v12, 2, v12
	s_lshl_b32 s22, s22, 6
	v_add3_u32 v17, 0, v10, v12
	v_add3_u32 v18, 0, v12, v10
	s_sub_i32 s27, s23, s22
	v_lshlrev_b32_e32 v12, 2, v20
	v_lshlrev_b32_e32 v10, 1, v22
	s_branch .LBB0_59

; __device__ __forceinline__ void tconv(const float* __restrict__ src, bf16_t* __restrict__ dst, int K, int N, const float* __restrict__ scale, float* tile, int& rot) {
;     ...
;         __syncthreads();
; #pragma unroll
;         for (int j = 0; j < 4; ++j) { tile[lr * 65 + lc + j] = v0[j]; tile[(lr + 32) * 65 + lc + j] = v1[j]; }
;         const int t2 = t + G;
;         if (t2 < nt) { const int kt2 = t2 / tn, k2 = kt2 << 6, n2 = (t2 - kt2 * tn) << 6; v0 = *(const f32x4*)(src + (size_t)(k2 + lr) * N + n2 + lc); v1 = *(const f32x4*)(src + (size_t)(k2 + lr + 32) * N + n2 + lc); }
.LBB0_59:
	s_add_i32 s40, s26, s72
	v_add_u32_e32 v13, 0x2080, v16
	s_cmpk_gt_i32 s40, 0x2bf
	s_barrier
	s_waitcnt vmcnt(2)
	ds_write2_b32 v15, v2, v3 offset1:1
	s_waitcnt vmcnt(1)
	ds_write2_b32 v13, v6, v7 offset1:1
	ds_write2_b32 v15, v4, v5 offset0:2 offset1:3
	v_add_u32_e32 v13, 0x2088, v16
	s_cselect_b64 s[22:23], -1, 0
	s_cmpk_lt_i32 s40, 0x2c0
	s_mov_b64 s[24:25], -1
	ds_write2_b32 v13, v8, v9 offset1:1
	s_cbranch_scc1 .LBB0_61
	s_add_i32 s41, s27, s74
	s_mov_b64 s[24:25], 0

; __device__ __forceinline__ int tid_v() { int t = threadIdx.x; asm volatile("" : "+v"(t)); return t; }
; __device__ __forceinline__ int bid_s() { int b = blockIdx.x; asm volatile("" : "+s"(b)); return b; }
; __device__ __forceinline__ void tconv(const float* __restrict__ src, bf16_t* __restrict__ dst, int K, int N, const float* __restrict__ scale, float* tile, int& rot) {
;     const int tk = K >> 6, tn = N >> 6, nt = tk * tn, G = gridDim.x;
;     const int tid = tid_v(), lr = tid >> 4, lc = (tid & 15) * 4;
;     const int sn = tid >> 3, sk = (tid & 7) * 8;
;     int t = (int)((bid_s() + G - (rot % G)) % G);
;     f32x4 v0, v1;
;     if (t < nt) { const int kt = t / tn, k0 = kt << 6, n0 = (t - kt * tn) << 6; v0 = *(const f32x4*)(src + (size_t)(k0 + lr) * N + n0 + lc); v1 = *(const f32x4*)(src + (size_t)(k0 + lr + 32) * N + n0 + lc); }
; __device__ __forceinline__ void phase0(unsigned char* shm) {
;     ...
;         tconv(IN(31) + (size_t)l * 256 * 1024, W + oWp, 256, 1024, nullptr, tile, rot);
.LBB0_63:
	s_add_i32 s21, s39, 0x1400
	s_mul_hi_u32 s22, s21, s36
	v_mov_b32_e32 v12, v179
	s_mov_b32 s20, s87
	s_mul_i32 s22, s22, s29
	s_load_dwordx2 s[18:19], s[0:1], 0xf8
	s_waitcnt lgkmcnt(0)
	s_sub_i32 s21, s21, s22
	s_add_i32 s20, s20, s72
	s_sub_i32 s22, s21, s29
	s_cmp_ge_u32 s21, s29
	s_cselect_b32 s21, s22, s21
	s_sub_i32 s22, s21, s29
	s_cmp_ge_u32 s21, s29
	s_cselect_b32 s21, s22, s21
	s_sub_i32 s20, s20, s21
	s_ashr_i32 s22, s20, 31
	s_abs_i32 s20, s20
	s_mul_hi_u32 s21, s20, s36
	s_mul_i32 s21, s21, s29
	s_sub_i32 s20, s20, s21
	s_sub_i32 s21, s20, s29
	s_cmp_ge_u32 s20, s29
	s_cselect_b32 s20, s21, s20
	s_sub_i32 s21, s20, s29
	s_cmp_ge_u32 s20, s29
	s_cselect_b32 s20, s21, s20
	s_xor_b32 s23, s20, s22
	s_sub_i32 s26, s23, s22
	s_cmp_gt_i32 s26, 63
	s_cbranch_scc1 .LBB0_70
	s_add_u32 s18, s18, s12
	s_addc_u32 s19, s19, s13
	s_add_u32 s20, s10, 0x2800000
	s_addc_u32 s21, s11, 0
	s_ashr_i32 s24, s26, 31
	s_lshr_b32 s24, s24, 28
	s_add_i32 s24, s26, s24
	v_ashrrev_i32_e32 v1, 4, v12
	s_waitcnt vmcnt(2)
	v_lshlrev_b32_e32 v2, 2, v12
	s_ashr_i32 s25, s24, 4
	v_and_b32_e32 v20, 60, v2
	v_lshl_add_u32 v2, s25, 6, v1
	s_lshl_b32 s24, s25, 10
	s_lshl_b32 s27, s26, 6
	v_ashrrev_i32_e32 v3, 31, v2
	s_sub_i32 s24, s27, s24
	v_lshlrev_b64 v[2:3], 12, v[2:3]
	v_lshl_add_u64 v[2:3], s[18:19], 0, v[2:3]
	s_ashr_i32 s25, s24, 31
	v_lshl_add_u64 v[2:3], s[24:25], 2, v[2:3]
	v_lshlrev_b32_e32 v10, 2, v20
	v_lshl_add_u64 v[14:15], v[2:3], 0, v[10:11]
	v_add_co_u32_e32 v16, vcc, s33, v14
	s_lshl_b32 s23, s23, 6
	s_nop 0
	v_addc_co_u32_e32 v17, vcc, 0, v15, vcc
	global_load_dwordx4 v[2:5], v[14:15], off
	global_load_dwordx4 v[6:9], v[16:17], off
	global_load_dword v52, v[14:15], off
	v_ashrrev_i32_e32 v14, 3, v12
	v_lshlrev_b32_e32 v12, 3, v12
	v_and_b32_e32 v22, 56, v12
	v_mul_lo_u32 v12, v1, s31
	v_add3_u32 v15, 0, v10, v12
	v_add3_u32 v16, 0, v12, v10
	v_mul_u32_u24_e32 v12, 0x41, v22
	v_lshlrev_b32_e32 v10, 2, v14
	v_lshlrev_b32_e32 v12, 2, v12
	s_lshl_b32 s22, s22, 6
	v_add3_u32 v17, 0, v10, v12
	v_add3_u32 v18, 0, v12, v10
	s_sub_i32 s27, s23, s22
	v_lshlrev_b32_e32 v12, 2, v20
	v_lshlrev_b32_e32 v10, 1, v22
	s_branch .LBB0_66

; __device__ __forceinline__ void tconv(const float* __restrict__ src, bf16_t* __restrict__ dst, int K, int N, const float* __restrict__ scale, float* tile, int& rot) {
;     ...
;         __syncthreads();
; #pragma unroll
;         for (int j = 0; j < 4; ++j) { tile[lr * 65 + lc + j] = v0[j]; tile[(lr + 32) * 65 + lc + j] = v1[j]; }
;         const int t2 = t + G;
;         if (t2 < nt) { const int kt2 = t2 / tn, k2 = kt2 << 6, n2 = (t2 - kt2 * tn) << 6; v0 = *(const f32x4*)(src + (size_t)(k2 + lr) * N + n2 + lc); v1 = *(const f32x4*)(src + (size_t)(k2 + lr + 32) * N + n2 + lc); }
.LBB0_66:
	s_add_i32 s40, s26, s72
	v_add_u32_e32 v13, 0x2080, v16
	s_cmp_gt_i32 s40, 63
	s_barrier
	s_waitcnt vmcnt(2)
	ds_write2_b32 v15, v2, v3 offset1:1
	s_waitcnt vmcnt(1)
	ds_write2_b32 v13, v6, v7 offset1:1
	ds_write2_b32 v15, v4, v5 offset0:2 offset1:3
	v_add_u32_e32 v13, 0x2088, v16
	s_cselect_b64 s[22:23], -1, 0
	s_cmp_lt_i32 s40, 64
	s_mov_b64 s[24:25], -1
	ds_write2_b32 v13, v8, v9 offset1:1
	s_cbranch_scc1 .LBB0_68
	s_add_i32 s41, s27, s74
	s_mov_b64 s[24:25], 0

; __device__ __forceinline__ int tid_v() { int t = threadIdx.x; asm volatile("" : "+v"(t)); return t; }
; __device__ __forceinline__ int bid_s() { int b = blockIdx.x; asm volatile("" : "+s"(b)); return b; }
; __device__ __forceinline__ void tconv(const float* __restrict__ src, bf16_t* __restrict__ dst, int K, int N, const float* __restrict__ scale, float* tile, int& rot) {
;     const int tk = K >> 6, tn = N >> 6, nt = tk * tn, G = gridDim.x;
;     const int tid = tid_v(), lr = tid >> 4, lc = (tid & 15) * 4;
;     const int sn = tid >> 3, sk = (tid & 7) * 8;
;     int t = (int)((bid_s() + G - (rot % G)) % G);
;     f32x4 v0, v1;
;     if (t < nt) { const int kt = t / tn, k0 = kt << 6, n0 = (t - kt * tn) << 6; v0 = *(const f32x4*)(src + (size_t)(k0 + lr) * N + n0 + lc); v1 = *(const f32x4*)(src + (size_t)(k0 + lr + 32) * N + n0 + lc); }
; __device__ __forceinline__ void phase0(unsigned char* shm) {
;     ...
;         tconv(IN(32) + (size_t)l * 1024 * 1024, W + oWg, 1024, 1024, IN(30) + l * 1024, tile, rot);
.LBB0_70:
	s_add_i32 s23, s39, 0x1440
	s_mul_hi_u32 s24, s23, s36
	s_load_dwordx2 s[18:19], s[0:1], 0x100
	s_waitcnt lgkmcnt(0)
	v_mov_b32_e32 v12, v179
	s_mov_b32 s22, s87
	s_mul_i32 s24, s24, s29
	s_load_dwordx2 s[20:21], s[0:1], 0xf0
	s_waitcnt lgkmcnt(0)
	s_sub_i32 s23, s23, s24
	s_add_i32 s22, s22, s72
	s_sub_i32 s24, s23, s29
	s_cmp_ge_u32 s23, s29
	s_cselect_b32 s23, s24, s23
	s_sub_i32 s24, s23, s29
	s_cmp_ge_u32 s23, s29
	s_cselect_b32 s23, s24, s23
	s_sub_i32 s23, s22, s23
	s_ashr_i32 s22, s23, 31
	s_abs_i32 s23, s23
	s_mul_hi_u32 s24, s23, s36
	s_mul_i32 s24, s24, s29
	s_sub_i32 s23, s23, s24
	s_sub_i32 s24, s23, s29
	s_cmp_ge_u32 s23, s29
	s_cselect_b32 s23, s24, s23
	s_sub_i32 s24, s23, s29
	s_cmp_ge_u32 s23, s29
	s_cselect_b32 s23, s24, s23
	s_xor_b32 s23, s23, s22
	s_sub_i32 s24, s23, s22
	s_cmpk_gt_i32 s24, 0xff
	s_cbranch_scc1 .LBB0_77
	s_lshl_b64 s[12:13], s[12:13], 2
	s_add_u32 s12, s18, s12
	s_addc_u32 s13, s19, s13
	s_add_u32 s18, s10, 0x2880000
	s_addc_u32 s19, s11, 0
	s_lshl_b64 s[26:27], s[4:5], 2
	s_add_u32 s26, s20, s26
	s_addc_u32 s27, s21, s27
	s_ashr_i32 s4, s24, 31
	s_lshr_b32 s4, s4, 28
	s_add_i32 s4, s24, s4
	v_ashrrev_i32_e32 v1, 4, v12
	s_waitcnt vmcnt(2)
	v_lshlrev_b32_e32 v2, 2, v12
	s_ashr_i32 s4, s4, 4
	v_and_b32_e32 v14, 60, v2
	v_lshl_add_u32 v2, s4, 6, v1
	s_lshl_b32 s25, s4, 10
	s_lshl_b32 s40, s24, 6
	v_ashrrev_i32_e32 v3, 31, v2
	s_sub_i32 s40, s40, s25
	v_lshlrev_b64 v[2:3], 12, v[2:3]
	v_lshl_add_u64 v[2:3], s[12:13], 0, v[2:3]
	s_ashr_i32 s41, s40, 31
	v_lshl_add_u64 v[2:3], s[40:41], 2, v[2:3]
	v_lshlrev_b32_e32 v10, 2, v14
	v_lshl_add_u64 v[16:17], v[2:3], 0, v[10:11]
	v_add_co_u32_e32 v18, vcc, s33, v16
	v_ashrrev_i32_e32 v24, 3, v12
	s_nop 0
	v_addc_co_u32_e32 v19, vcc, 0, v17, vcc
	global_load_dwordx4 v[2:5], v[16:17], off
	global_load_dwordx4 v[6:9], v[18:19], off
	global_load_dword v52, v[16:17], off
	v_lshlrev_b32_e32 v12, 3, v12
	v_and_b32_e32 v16, 56, v12
	v_mul_lo_u32 v12, v1, s31
	v_add3_u32 v25, 0, v10, v12
	v_add3_u32 v26, 0, v12, v10
	v_lshlrev_b32_e32 v10, 2, v16
	s_cmp_lg_u64 s[20:21], 0
	v_lshl_add_u64 v[12:13], s[26:27], 0, v[10:11]
	v_mul_u32_u24_e32 v10, 0x41, v16
	v_lshlrev_b32_e32 v15, 2, v24
	s_cselect_b64 s[20:21], -1, 0
	v_lshlrev_b32_e32 v10, 2, v10
	s_lshl_b32 s4, s23, 6
	s_lshl_b32 s22, s22, 6
	v_add3_u32 v27, 0, v15, v10
	v_add3_u32 v28, 0, v10, v15
	s_sub_i32 s4, s4, s22
	v_lshlrev_b32_e32 v14, 2, v14
	v_lshlrev_b32_e32 v10, 1, v16
	s_branch .LBB0_73

; __device__ __forceinline__ u32x4 pack8(const f32x4& v0, const f32x4& v1) { u32x4 w; w.x = cvt_pk_bf16(v0[0], v0[1]); w.y = cvt_pk_bf16(v0[2], v0[3]); w.z = cvt_pk_bf16(v1[0], v1[1]); w.w = cvt_pk_bf16(v1[2], v1[3]); return w; }
; __device__ __forceinline__ void tconv(const float* __restrict__ src, bf16_t* __restrict__ dst, int K, int N, const float* __restrict__ scale, float* tile, int& rot) {
;     ...
;     for (; t < nt; t += G) {
;         const int kt = t / tn, k0 = kt << 6, n0 = (t - kt * tn) << 6;
;         __syncthreads();
; #pragma unroll
;         for (int j = 0; j < 4; ++j) { tile[lr * 65 + lc + j] = v0[j]; tile[(lr + 32) * 65 + lc + j] = v1[j]; }
;         const int t2 = t + G;
;         if (t2 < nt) { const int kt2 = t2 / tn, k2 = kt2 << 6, n2 = (t2 - kt2 * tn) << 6; v0 = *(const f32x4*)(src + (size_t)(k2 + lr) * N + n2 + lc); v1 = *(const f32x4*)(src + (size_t)(k2 + lr + 32) * N + n2 + lc); }
;         __syncthreads();
;         f32x4 a, bb;
; #pragma unroll
;         for (int j = 0; j < 4; ++j) { a[j] = tile[(sk + j) * 65 + sn]; bb[j] = tile[(sk + 4 + j) * 65 + sn]; }
;         if (scale) { a *= *(const f32x4*)(scale + k0 + sk); bb *= *(const f32x4*)(scale + k0 + sk + 4); }
;         *(u32x4*)(dst + (size_t)(n0 + sn) * K + k0 + sk) = pack8(a, bb);
;     }
; __device__ __forceinline__ void phase0(unsigned char* shm) {
;     ...
;         for (int g = 0; g < 4; ++g) tconv(IN(4) + (size_t)(l * 4 + g) * 128 * 128, W + oPw + (size_t)g * 16384, 128, 128, nullptr, tile, rot);
.LBB0_73:
	s_ashr_i32 s101, s24, 31
	s_lshr_b32 s101, s101, 28
	s_add_i32 s100, s24, s101
	s_ashr_i32 s100, s100, 4
	s_lshl_b32 s100, s100, 6
	s_ashr_i32 s101, s100, 31
	v_lshl_add_u64 v[38:39], s[100:101], 2, v[12:13]
	global_load_dwordx4 v[30:33], v[38:39], off
	global_load_dwordx4 v[34:37], v[38:39], off offset:16
	s_add_i32 s26, s24, s72
	s_cmpk_gt_i32 s26, 0xff
	v_add_u32_e32 v15, 0x2080, v26
	s_cselect_b64 s[22:23], -1, 0
	s_barrier
	s_waitcnt vmcnt(4)
	ds_write2_b32 v25, v2, v3 offset1:1
	s_waitcnt vmcnt(3)
	ds_write2_b32 v15, v6, v7 offset1:1
	ds_write2_b32 v25, v4, v5 offset0:2 offset1:3
	v_add_u32_e32 v15, 0x2088, v26
	s_and_b64 vcc, exec, s[22:23]
	ds_write2_b32 v15, v8, v9 offset1:1
	s_cbranch_vccnz .Ltc_drain_73
	s_ashr_i32 s25, s26, 31
	s_lshr_b32 s25, s25, 28
	s_add_i32 s25, s26, s25
	s_ashr_i32 s25, s25, 4
	v_lshl_add_u32 v2, s25, 6, v1
	s_add_i32 s27, s74, s4
	s_lshl_b32 s40, s25, 10
	v_ashrrev_i32_e32 v3, 31, v2
	s_sub_i32 s40, s27, s40
	v_lshlrev_b64 v[2:3], 12, v[2:3]
	v_lshl_add_u64 v[2:3], s[12:13], 0, v[2:3]
	s_ashr_i32 s41, s40, 31
	v_lshl_add_u64 v[2:3], s[40:41], 2, v[2:3]
	v_mov_b32_e32 v15, v11
	v_lshl_add_u64 v[16:17], v[2:3], 0, v[14:15]
	v_add_co_u32_e32 v18, vcc, 0x20000, v16
	s_nop 1
	v_addc_co_u32_e32 v19, vcc, 0, v17, vcc
	global_load_dwordx4 v[2:5], v[16:17], off
	global_load_dwordx4 v[6:9], v[18:19], off
.LBB0_75:
	v_add_u32_e32 v15, 0x400, v28
	s_ashr_i32 s25, s24, 31
	s_waitcnt lgkmcnt(0)
	s_barrier
	ds_read2_b32 v[16:17], v27 offset1:65
	ds_read2_b32 v[18:19], v15 offset0:4 offset1:69
	ds_read2_b32 v[20:21], v27 offset0:130 offset1:195
	ds_read2_b32 v[22:23], v15 offset0:134 offset1:199
	s_lshr_b32 s25, s25, 28
	s_add_i32 s24, s24, s25
	s_ashr_i32 s27, s24, 4
	s_lshl_b32 s24, s27, 6
	s_andn2_b64 vcc, exec, s[20:21]
	s_ashr_i32 s25, s24, 31
	s_cbranch_vccnz .LBB0_72
	s_waitcnt vmcnt(3) lgkmcnt(1)
	v_pk_mul_f32 v[20:21], v[20:21], v[32:33]
	v_pk_mul_f32 v[16:17], v[16:17], v[30:31]
	s_waitcnt vmcnt(2) lgkmcnt(0)
	v_pk_mul_f32 v[22:23], v[22:23], v[36:37]
	v_pk_mul_f32 v[18:19], v[18:19], v[34:35]
	s_branch .LBB0_72
.LBB0_77:
	s_add_i32 s13, s39, 0x1540
	s_mul_hi_u32 s20, s13, s36
	v_mov_b32_e32 v12, v179
	s_mov_b32 s12, s87
	s_mul_i32 s20, s20, s29
	s_load_dwordx2 s[18:19], s[0:1], 32
	s_waitcnt lgkmcnt(0)
	s_sub_i32 s13, s13, s20
	s_lshl_b32 s4, s2, 16
	s_add_i32 s12, s12, s72
	s_sub_i32 s20, s13, s29
	s_cmp_ge_u32 s13, s29
	s_cselect_b32 s13, s20, s13
	s_sub_i32 s20, s13, s29
	s_cmp_ge_u32 s13, s29
	s_cselect_b32 s13, s20, s13
	s_sub_i32 s12, s12, s13
	s_ashr_i32 s20, s12, 31
	s_abs_i32 s12, s12
	s_mul_hi_u32 s13, s12, s36
	s_mul_i32 s13, s13, s29
	s_sub_i32 s12, s12, s13
	s_sub_i32 s13, s12, s29
	s_cmp_ge_u32 s12, s29
	s_cselect_b32 s12, s13, s12
	s_sub_i32 s13, s12, s29
	s_cmp_ge_u32 s12, s29
	s_cselect_b32 s12, s13, s12
	s_xor_b32 s21, s12, s20
	s_sub_i32 s24, s21, s20
	s_cmp_lt_i32 s24, 4
	s_cbranch_scc0 .LBB0_84
	s_add_u32 s12, s10, 0x2a80000
	s_addc_u32 s13, s11, 0
	s_lshl_b64 s[22:23], s[4:5], 2
	s_add_u32 s18, s18, s22
	s_addc_u32 s19, s19, s23
	s_lshr_b32 s22, s24, 31
	s_add_i32 s22, s24, s22
	v_ashrrev_i32_e32 v1, 4, v12
	s_waitcnt vmcnt(2)
	v_lshlrev_b32_e32 v2, 2, v12
	s_ashr_i32 s23, s22, 1
	v_and_b32_e32 v20, 60, v2
	v_lshl_add_u32 v2, s23, 6, v1
	s_lshl_b32 s22, s23, 7
	s_lshl_b32 s25, s24, 6
	v_ashrrev_i32_e32 v3, 31, v2
	s_sub_i32 s22, s25, s22
	v_lshlrev_b64 v[2:3], 9, v[2:3]
	v_lshl_add_u64 v[2:3], s[18:19], 0, v[2:3]
	s_ashr_i32 s23, s22, 31
	v_lshl_add_u64 v[2:3], s[22:23], 2, v[2:3]
	v_lshlrev_b32_e32 v10, 2, v20
	v_lshl_add_u64 v[14:15], v[2:3], 0, v[10:11]
	v_add_co_u32_e32 v16, vcc, s37, v14
	s_lshl_b32 s21, s21, 6
	s_nop 0
	v_addc_co_u32_e32 v17, vcc, 0, v15, vcc
	global_load_dwordx4 v[2:5], v[14:15], off
	global_load_dwordx4 v[6:9], v[16:17], off
	global_load_dword v52, v[14:15], off
	v_ashrrev_i32_e32 v14, 3, v12
	v_lshlrev_b32_e32 v12, 3, v12
	v_and_b32_e32 v22, 56, v12
	v_mul_lo_u32 v12, v1, s31
	v_add3_u32 v15, 0, v10, v12
	v_add3_u32 v16, 0, v12, v10
	v_mul_u32_u24_e32 v12, 0x41, v22
	v_lshlrev_b32_e32 v10, 2, v14
	v_lshlrev_b32_e32 v12, 2, v12
	s_lshl_b32 s20, s20, 6
	v_add3_u32 v17, 0, v10, v12
	v_add3_u32 v18, 0, v12, v10
	s_sub_i32 s25, s21, s20
	v_lshlrev_b32_e32 v12, 2, v20
	v_lshlrev_b32_e32 v10, 1, v22
	s_branch .LBB0_80

; __device__ __forceinline__ void tconv(const float* __restrict__ src, bf16_t* __restrict__ dst, int K, int N, const float* __restrict__ scale, float* tile, int& rot) {
;     ...
;         __syncthreads();
; #pragma unroll
;         for (int j = 0; j < 4; ++j) { tile[lr * 65 + lc + j] = v0[j]; tile[(lr + 32) * 65 + lc + j] = v1[j]; }
;         const int t2 = t + G;
;         if (t2 < nt) { const int kt2 = t2 / tn, k2 = kt2 << 6, n2 = (t2 - kt2 * tn) << 6; v0 = *(const f32x4*)(src + (size_t)(k2 + lr) * N + n2 + lc); v1 = *(const f32x4*)(src + (size_t)(k2 + lr + 32) * N + n2 + lc); }
.LBB0_80:
	s_add_i32 s26, s24, s72
	v_add_u32_e32 v13, 0x2080, v16
	s_cmp_gt_i32 s26, 3
	s_barrier
	s_waitcnt vmcnt(2)
	ds_write2_b32 v15, v2, v3 offset1:1
	s_waitcnt vmcnt(1)
	ds_write2_b32 v13, v6, v7 offset1:1
	ds_write2_b32 v15, v4, v5 offset0:2 offset1:3
	v_add_u32_e32 v13, 0x2088, v16
	s_cselect_b64 s[20:21], -1, 0
	s_cmp_lt_i32 s26, 4
	s_mov_b64 s[22:23], -1
	ds_write2_b32 v13, v8, v9 offset1:1
	s_cbranch_scc1 .LBB0_82
	s_add_i32 s27, s25, s74
	s_mov_b64 s[22:23], 0

; __device__ __forceinline__ int tid_v() { int t = threadIdx.x; asm volatile("" : "+v"(t)); return t; }
; __device__ __forceinline__ int bid_s() { int b = blockIdx.x; asm volatile("" : "+s"(b)); return b; }
; __device__ __forceinline__ void tconv(const float* __restrict__ src, bf16_t* __restrict__ dst, int K, int N, const float* __restrict__ scale, float* tile, int& rot) {
;     const int tk = K >> 6, tn = N >> 6, nt = tk * tn, G = gridDim.x;
;     const int tid = tid_v(), lr = tid >> 4, lc = (tid & 15) * 4;
;     const int sn = tid >> 3, sk = (tid & 7) * 8;
;     int t = (int)((bid_s() + G - (rot % G)) % G);
;     f32x4 v0, v1;
;     if (t < nt) { const int kt = t / tn, k0 = kt << 6, n0 = (t - kt * tn) << 6; v0 = *(const f32x4*)(src + (size_t)(k0 + lr) * N + n0 + lc); v1 = *(const f32x4*)(src + (size_t)(k0 + lr + 32) * N + n0 + lc); }
; __device__ __forceinline__ void phase0(unsigned char* shm) {
;     ...
;         for (int g = 0; g < 4; ++g) tconv(IN(4) + (size_t)(l * 4 + g) * 128 * 128, W + oPw + (size_t)g * 16384, 128, 128, nullptr, tile, rot);
.LBB0_84:
	s_add_i32 s19, s39, 0x1544
	s_mul_hi_u32 s20, s19, s36
	v_mov_b32_e32 v12, v179
	s_mov_b32 s18, s87
	s_mul_i32 s20, s20, s29
	s_load_dwordx2 s[12:13], s[0:1], 32
	s_waitcnt lgkmcnt(0)
	s_sub_i32 s19, s19, s20
	s_add_i32 s18, s18, s72
	s_sub_i32 s20, s19, s29
	s_cmp_ge_u32 s19, s29
	s_cselect_b32 s19, s20, s19
	s_sub_i32 s20, s19, s29
	s_cmp_ge_u32 s19, s29
	s_cselect_b32 s19, s20, s19
	s_sub_i32 s18, s18, s19
	s_ashr_i32 s20, s18, 31
	s_abs_i32 s18, s18
	s_mul_hi_u32 s19, s18, s36
	s_mul_i32 s19, s19, s29
	s_sub_i32 s18, s18, s19
	s_sub_i32 s19, s18, s29
	s_cmp_ge_u32 s18, s29
	s_cselect_b32 s18, s19, s18
	s_sub_i32 s19, s18, s29
	s_cmp_ge_u32 s18, s29
	s_cselect_b32 s18, s19, s18
	s_xor_b32 s21, s18, s20
	s_sub_i32 s24, s21, s20
	s_cmp_gt_i32 s24, 3
	s_cbranch_scc1 .LBB0_91
	s_lshl_b64 s[18:19], s[4:5], 2
	s_add_u32 s12, s12, s18
	s_addc_u32 s13, s13, s19
	s_add_u32 s12, s12, 0x10000
	s_addc_u32 s13, s13, 0
	s_add_u32 s18, s10, 0x2a88000
	s_addc_u32 s19, s11, 0
	s_lshr_b32 s22, s24, 31
	s_add_i32 s22, s24, s22
	v_ashrrev_i32_e32 v1, 4, v12
	s_waitcnt vmcnt(2)
	v_lshlrev_b32_e32 v2, 2, v12
	s_ashr_i32 s23, s22, 1
	v_and_b32_e32 v20, 60, v2
	v_lshl_add_u32 v2, s23, 6, v1
	s_lshl_b32 s22, s23, 7
	s_lshl_b32 s25, s24, 6
	v_ashrrev_i32_e32 v3, 31, v2
	s_sub_i32 s22, s25, s22
	v_lshlrev_b64 v[2:3], 9, v[2:3]
	v_lshl_add_u64 v[2:3], s[12:13], 0, v[2:3]
	s_ashr_i32 s23, s22, 31
	v_lshl_add_u64 v[2:3], s[22:23], 2, v[2:3]
	v_lshlrev_b32_e32 v10, 2, v20
	v_lshl_add_u64 v[14:15], v[2:3], 0, v[10:11]
	v_add_co_u32_e32 v16, vcc, s37, v14
	s_lshl_b32 s21, s21, 6
	s_nop 0
	v_addc_co_u32_e32 v17, vcc, 0, v15, vcc
	global_load_dwordx4 v[2:5], v[14:15], off
	global_load_dwordx4 v[6:9], v[16:17], off
	global_load_dword v52, v[14:15], off
	v_ashrrev_i32_e32 v14, 3, v12
	v_lshlrev_b32_e32 v12, 3, v12
	v_and_b32_e32 v22, 56, v12
	v_mul_lo_u32 v12, v1, s31
	v_add3_u32 v15, 0, v10, v12
	v_add3_u32 v16, 0, v12, v10
	v_mul_u32_u24_e32 v12, 0x41, v22
	v_lshlrev_b32_e32 v10, 2, v14
	v_lshlrev_b32_e32 v12, 2, v12
	s_lshl_b32 s20, s20, 6
	v_add3_u32 v17, 0, v10, v12
	v_add3_u32 v18, 0, v12, v10
	s_sub_i32 s25, s21, s20
	v_lshlrev_b32_e32 v12, 2, v20
	v_lshlrev_b32_e32 v10, 1, v22
	s_branch .LBB0_87

; __device__ __forceinline__ int tid_v() { int t = threadIdx.x; asm volatile("" : "+v"(t)); return t; }
; __device__ __forceinline__ int bid_s() { int b = blockIdx.x; asm volatile("" : "+s"(b)); return b; }
; __device__ __forceinline__ void tconv(const float* __restrict__ src, bf16_t* __restrict__ dst, int K, int N, const float* __restrict__ scale, float* tile, int& rot) {
;     const int tk = K >> 6, tn = N >> 6, nt = tk * tn, G = gridDim.x;
;     const int tid = tid_v(), lr = tid >> 4, lc = (tid & 15) * 4;
;     const int sn = tid >> 3, sk = (tid & 7) * 8;
;     int t = (int)((bid_s() + G - (rot % G)) % G);
;     f32x4 v0, v1;
;     if (t < nt) { const int kt = t / tn, k0 = kt << 6, n0 = (t - kt * tn) << 6; v0 = *(const f32x4*)(src + (size_t)(k0 + lr) * N + n0 + lc); v1 = *(const f32x4*)(src + (size_t)(k0 + lr + 32) * N + n0 + lc); }
; __device__ __forceinline__ void phase0(unsigned char* shm) {
;     ...
;         for (int g = 0; g < 4; ++g) tconv(IN(4) + (size_t)(l * 4 + g) * 128 * 128, W + oPw + (size_t)g * 16384, 128, 128, nullptr, tile, rot);
.LBB0_91:
	s_add_i32 s19, s39, 0x1548
	s_mul_hi_u32 s20, s19, s36
	v_mov_b32_e32 v12, v179
	s_mov_b32 s18, s87
	s_mul_i32 s20, s20, s29
	s_load_dwordx2 s[12:13], s[0:1], 32
	s_waitcnt lgkmcnt(0)
	s_sub_i32 s19, s19, s20
	s_add_i32 s18, s18, s72
	s_sub_i32 s20, s19, s29
	s_cmp_ge_u32 s19, s29
	s_cselect_b32 s19, s20, s19
	s_sub_i32 s20, s19, s29
	s_cmp_ge_u32 s19, s29
	s_cselect_b32 s19, s20, s19
	s_sub_i32 s18, s18, s19
	s_ashr_i32 s20, s18, 31
	s_abs_i32 s18, s18
	s_mul_hi_u32 s19, s18, s36
	s_mul_i32 s19, s19, s29
	s_sub_i32 s18, s18, s19
	s_sub_i32 s19, s18, s29
	s_cmp_ge_u32 s18, s29
	s_cselect_b32 s18, s19, s18
	s_sub_i32 s19, s18, s29
	s_cmp_ge_u32 s18, s29
	s_cselect_b32 s18, s19, s18
	s_xor_b32 s21, s18, s20
	s_sub_i32 s24, s21, s20
	s_cmp_gt_i32 s24, 3
	s_cbranch_scc1 .LBB0_98
	s_lshl_b64 s[18:19], s[4:5], 2
	s_add_u32 s12, s12, s18
	s_addc_u32 s13, s13, s19
	s_add_u32 s12, s12, 0x20000
	s_addc_u32 s13, s13, 0
	s_add_u32 s18, s10, 0x2a90000
	s_addc_u32 s19, s11, 0
	s_lshr_b32 s22, s24, 31
	s_add_i32 s22, s24, s22
	v_ashrrev_i32_e32 v1, 4, v12
	s_waitcnt vmcnt(2)
	v_lshlrev_b32_e32 v2, 2, v12
	s_ashr_i32 s23, s22, 1
	v_and_b32_e32 v20, 60, v2
	v_lshl_add_u32 v2, s23, 6, v1
	s_lshl_b32 s22, s23, 7
	s_lshl_b32 s25, s24, 6
	v_ashrrev_i32_e32 v3, 31, v2
	s_sub_i32 s22, s25, s22
	v_lshlrev_b64 v[2:3], 9, v[2:3]
	v_lshl_add_u64 v[2:3], s[12:13], 0, v[2:3]
	s_ashr_i32 s23, s22, 31
	v_lshl_add_u64 v[2:3], s[22:23], 2, v[2:3]
	v_lshlrev_b32_e32 v10, 2, v20
	v_lshl_add_u64 v[14:15], v[2:3], 0, v[10:11]
	v_add_co_u32_e32 v16, vcc, s37, v14
	s_lshl_b32 s21, s21, 6
	s_nop 0
	v_addc_co_u32_e32 v17, vcc, 0, v15, vcc
	global_load_dwordx4 v[2:5], v[14:15], off
	global_load_dwordx4 v[6:9], v[16:17], off
	global_load_dword v52, v[14:15], off
	v_ashrrev_i32_e32 v14, 3, v12
	v_lshlrev_b32_e32 v12, 3, v12
	v_and_b32_e32 v22, 56, v12
	v_mul_lo_u32 v12, v1, s31
	v_add3_u32 v15, 0, v10, v12
	v_add3_u32 v16, 0, v12, v10
	v_mul_u32_u24_e32 v12, 0x41, v22
	v_lshlrev_b32_e32 v10, 2, v14
	v_lshlrev_b32_e32 v12, 2, v12
	s_lshl_b32 s20, s20, 6
	v_add3_u32 v17, 0, v10, v12
	v_add3_u32 v18, 0, v12, v10
	s_sub_i32 s25, s21, s20
	v_lshlrev_b32_e32 v12, 2, v20
	v_lshlrev_b32_e32 v10, 1, v22
	s_branch .LBB0_94

; __device__ __forceinline__ int tid_v() { int t = threadIdx.x; asm volatile("" : "+v"(t)); return t; }
; __device__ __forceinline__ int bid_s() { int b = blockIdx.x; asm volatile("" : "+s"(b)); return b; }
; __device__ __forceinline__ void tconv(const float* __restrict__ src, bf16_t* __restrict__ dst, int K, int N, const float* __restrict__ scale, float* tile, int& rot) {
;     const int tk = K >> 6, tn = N >> 6, nt = tk * tn, G = gridDim.x;
;     const int tid = tid_v(), lr = tid >> 4, lc = (tid & 15) * 4;
;     const int sn = tid >> 3, sk = (tid & 7) * 8;
;     int t = (int)((bid_s() + G - (rot % G)) % G);
;     f32x4 v0, v1;
;     if (t < nt) { const int kt = t / tn, k0 = kt << 6, n0 = (t - kt * tn) << 6; v0 = *(const f32x4*)(src + (size_t)(k0 + lr) * N + n0 + lc); v1 = *(const f32x4*)(src + (size_t)(k0 + lr + 32) * N + n0 + lc); }
; __device__ __forceinline__ void phase0(unsigned char* shm) {
;     ...
;         for (int g = 0; g < 4; ++g) tconv(IN(4) + (size_t)(l * 4 + g) * 128 * 128, W + oPw + (size_t)g * 16384, 128, 128, nullptr, tile, rot);
.LBB0_98:
	s_add_i32 s19, s39, 0x154c
	s_mul_hi_u32 s20, s19, s36
	v_mov_b32_e32 v12, v179
	s_mov_b32 s18, s87
	s_mul_i32 s20, s20, s29
	s_load_dwordx2 s[12:13], s[0:1], 32
	s_waitcnt lgkmcnt(0)
	s_sub_i32 s19, s19, s20
	s_add_i32 s18, s18, s72
	s_sub_i32 s20, s19, s29
	s_cmp_ge_u32 s19, s29
	s_cselect_b32 s19, s20, s19
	s_sub_i32 s20, s19, s29
	s_cmp_ge_u32 s19, s29
	s_cselect_b32 s19, s20, s19
	s_sub_i32 s18, s18, s19
	s_ashr_i32 s20, s18, 31
	s_abs_i32 s18, s18
	s_mul_hi_u32 s19, s18, s36
	s_mul_i32 s19, s19, s29
	s_sub_i32 s18, s18, s19
	s_sub_i32 s19, s18, s29
	s_cmp_ge_u32 s18, s29
	s_cselect_b32 s18, s19, s18
	s_sub_i32 s19, s18, s29
	s_cmp_ge_u32 s18, s29
	s_cselect_b32 s18, s19, s18
	s_xor_b32 s21, s18, s20
	s_sub_i32 s24, s21, s20
	s_cmp_gt_i32 s24, 3
	s_cbranch_scc1 .LBB0_105
	s_lshl_b64 s[18:19], s[4:5], 2
	s_add_u32 s4, s12, s18
	s_addc_u32 s13, s13, s19
	s_add_u32 s12, s4, 0x30000
	s_addc_u32 s13, s13, 0
	s_add_u32 s18, s10, 0x2a98000
	s_addc_u32 s19, s11, 0
	s_lshr_b32 s4, s24, 31
	s_add_i32 s4, s24, s4
	v_ashrrev_i32_e32 v1, 4, v12
	s_waitcnt vmcnt(2)
	v_lshlrev_b32_e32 v2, 2, v12
	s_ashr_i32 s4, s4, 1
	v_and_b32_e32 v20, 60, v2
	v_lshl_add_u32 v2, s4, 6, v1
	s_lshl_b32 s22, s4, 7
	s_lshl_b32 s23, s24, 6
	v_ashrrev_i32_e32 v3, 31, v2
	s_sub_i32 s22, s23, s22
	v_lshlrev_b64 v[2:3], 9, v[2:3]
	v_lshl_add_u64 v[2:3], s[12:13], 0, v[2:3]
	s_ashr_i32 s23, s22, 31
	v_lshl_add_u64 v[2:3], s[22:23], 2, v[2:3]
	v_lshlrev_b32_e32 v10, 2, v20
	v_lshl_add_u64 v[14:15], v[2:3], 0, v[10:11]
	v_add_co_u32_e32 v16, vcc, s37, v14
	s_lshl_b32 s4, s21, 6
	s_nop 0
	v_addc_co_u32_e32 v17, vcc, 0, v15, vcc
	global_load_dwordx4 v[2:5], v[14:15], off
	global_load_dwordx4 v[6:9], v[16:17], off
	global_load_dword v52, v[14:15], off
	v_ashrrev_i32_e32 v14, 3, v12
	v_lshlrev_b32_e32 v12, 3, v12
	v_and_b32_e32 v22, 56, v12
	v_mul_lo_u32 v12, v1, s31
	v_add3_u32 v15, 0, v10, v12
	v_add3_u32 v16, 0, v12, v10
	v_mul_u32_u24_e32 v12, 0x41, v22
	v_lshlrev_b32_e32 v10, 2, v14
	v_lshlrev_b32_e32 v12, 2, v12
	s_lshl_b32 s20, s20, 6
	v_add3_u32 v17, 0, v10, v12
	v_add3_u32 v18, 0, v12, v10
	s_sub_i32 s4, s4, s20
	v_lshlrev_b32_e32 v12, 2, v20
	v_lshlrev_b32_e32 v10, 1, v22
	s_branch .LBB0_101

; __device__ __forceinline__ void tconv(const float* __restrict__ src, bf16_t* __restrict__ dst, int K, int N, const float* __restrict__ scale, float* tile, int& rot) {
;     ...
;         __syncthreads();
; #pragma unroll
;         for (int j = 0; j < 4; ++j) { tile[lr * 65 + lc + j] = v0[j]; tile[(lr + 32) * 65 + lc + j] = v1[j]; }
;         const int t2 = t + G;
;         if (t2 < nt) { const int kt2 = t2 / tn, k2 = kt2 << 6, n2 = (t2 - kt2 * tn) << 6; v0 = *(const f32x4*)(src + (size_t)(k2 + lr) * N + n2 + lc); v1 = *(const f32x4*)(src + (size_t)(k2 + lr + 32) * N + n2 + lc); }
.LBB0_101:
	s_add_i32 s25, s24, s72
	v_add_u32_e32 v13, 0x2080, v16
	s_cmp_gt_i32 s25, 3
	s_barrier
	s_waitcnt vmcnt(2)
	ds_write2_b32 v15, v2, v3 offset1:1
	s_waitcnt vmcnt(1)
	ds_write2_b32 v13, v6, v7 offset1:1
	ds_write2_b32 v15, v4, v5 offset0:2 offset1:3
	v_add_u32_e32 v13, 0x2088, v16
	s_cselect_b64 s[20:21], -1, 0
	s_cmp_lt_i32 s25, 4
	s_mov_b64 s[22:23], -1
	ds_write2_b32 v13, v8, v9 offset1:1
	s_cbranch_scc1 .LBB0_103
	s_add_i32 s26, s4, s74
	s_mov_b64 s[22:23], 0

; __device__ __forceinline__ int tid_v() { int t = threadIdx.x; asm volatile("" : "+v"(t)); return t; }
; __device__ __forceinline__ int bid_s() { int b = blockIdx.x; asm volatile("" : "+s"(b)); return b; }
; __device__ __forceinline__ void tconv(const float* __restrict__ src, bf16_t* __restrict__ dst, int K, int N, const float* __restrict__ scale, float* tile, int& rot) {
;     const int tk = K >> 6, tn = N >> 6, nt = tk * tn, G = gridDim.x;
;     const int tid = tid_v(), lr = tid >> 4, lc = (tid & 15) * 4;
;     const int sn = tid >> 3, sk = (tid & 7) * 8;
;     int t = (int)((bid_s() + G - (rot % G)) % G);
;     f32x4 v0, v1;
;     if (t < nt) { const int kt = t / tn, k0 = kt << 6, n0 = (t - kt * tn) << 6; v0 = *(const f32x4*)(src + (size_t)(k0 + lr) * N + n0 + lc); v1 = *(const f32x4*)(src + (size_t)(k0 + lr + 32) * N + n0 + lc); }
; __device__ __forceinline__ void phase0(unsigned char* shm) {
;     ...
;         tconv(IN(8) + (size_t)l * 64 * 512, W + oW2, 64, 512, nullptr, tile, rot);
.LBB0_105:
	s_add_i32 s20, s39, 0x1550
	s_mul_hi_u32 s21, s20, s36
	v_mov_b32_e32 v12, v179
	s_mov_b32 s4, s87
	s_mul_i32 s21, s21, s29
	s_load_dwordx2 s[18:19], s[0:1], 64
	s_waitcnt lgkmcnt(0)
	s_sub_i32 s20, s20, s21
	s_lshl_b64 s[12:13], s[2:3], 15
	s_add_i32 s4, s4, s72
	s_sub_i32 s21, s20, s29
	s_cmp_ge_u32 s20, s29
	s_cselect_b32 s20, s21, s20
	s_sub_i32 s21, s20, s29
	s_cmp_ge_u32 s20, s29
	s_cselect_b32 s20, s21, s20
	s_sub_i32 s4, s4, s20
	s_ashr_i32 s22, s4, 31
	s_abs_i32 s4, s4
	s_mul_hi_u32 s20, s4, s36
	s_mul_i32 s20, s20, s29
	s_sub_i32 s4, s4, s20
	s_sub_i32 s20, s4, s29
	s_cmp_ge_u32 s4, s29
	s_cselect_b32 s4, s20, s4
	s_sub_i32 s20, s4, s29
	s_cmp_ge_u32 s4, s29
	s_cselect_b32 s4, s20, s4
	s_xor_b32 s23, s4, s22
	s_sub_i32 s4, s23, s22
	s_cmp_lt_i32 s4, 8
	s_cbranch_scc0 .LBB0_112
	s_lshl_b64 s[20:21], s[12:13], 2
	s_add_u32 s18, s18, s20
	s_addc_u32 s19, s19, s21
	s_add_u32 s20, s10, 0x2aa0000
	s_addc_u32 s21, s11, 0
	s_ashr_i32 s24, s4, 31
	s_lshr_b32 s24, s24, 29
	s_add_i32 s24, s4, s24
	v_ashrrev_i32_e32 v1, 4, v12
	s_waitcnt vmcnt(2)
	v_lshlrev_b32_e32 v2, 2, v12
	s_ashr_i32 s25, s24, 3
	v_and_b32_e32 v20, 60, v2
	v_lshl_add_u32 v2, s25, 6, v1
	s_lshl_b32 s24, s25, 9
	s_lshl_b32 s26, s4, 6
	v_ashrrev_i32_e32 v3, 31, v2
	s_sub_i32 s24, s26, s24
	v_lshlrev_b64 v[2:3], 11, v[2:3]
	v_lshl_add_u64 v[2:3], s[18:19], 0, v[2:3]
	s_ashr_i32 s25, s24, 31
	v_lshl_add_u64 v[2:3], s[24:25], 2, v[2:3]
	v_lshlrev_b32_e32 v10, 2, v20
	v_lshl_add_u64 v[14:15], v[2:3], 0, v[10:11]
	v_add_co_u32_e32 v16, vcc, s38, v14
	s_lshl_b32 s23, s23, 6
	s_nop 0
	v_addc_co_u32_e32 v17, vcc, 0, v15, vcc
	global_load_dwordx4 v[2:5], v[14:15], off
	global_load_dwordx4 v[6:9], v[16:17], off
	global_load_dword v52, v[14:15], off
	v_ashrrev_i32_e32 v14, 3, v12
	v_lshlrev_b32_e32 v12, 3, v12
	v_and_b32_e32 v22, 56, v12
	v_mul_lo_u32 v12, v1, s31
	v_add3_u32 v15, 0, v10, v12
	v_add3_u32 v16, 0, v12, v10
	v_mul_u32_u24_e32 v12, 0x41, v22
	v_lshlrev_b32_e32 v10, 2, v14
	v_lshlrev_b32_e32 v12, 2, v12
	s_lshl_b32 s22, s22, 6
	v_add3_u32 v17, 0, v10, v12
	v_add3_u32 v18, 0, v12, v10
	s_sub_i32 s26, s23, s22
	v_lshlrev_b32_e32 v12, 2, v20
	v_lshlrev_b32_e32 v10, 1, v22
	s_branch .LBB0_108

; __device__ __forceinline__ void tconv(const float* __restrict__ src, bf16_t* __restrict__ dst, int K, int N, const float* __restrict__ scale, float* tile, int& rot) {
;     ...
;         __syncthreads();
; #pragma unroll
;         for (int j = 0; j < 4; ++j) { tile[lr * 65 + lc + j] = v0[j]; tile[(lr + 32) * 65 + lc + j] = v1[j]; }
;         const int t2 = t + G;
;         if (t2 < nt) { const int kt2 = t2 / tn, k2 = kt2 << 6, n2 = (t2 - kt2 * tn) << 6; v0 = *(const f32x4*)(src + (size_t)(k2 + lr) * N + n2 + lc); v1 = *(const f32x4*)(src + (size_t)(k2 + lr + 32) * N + n2 + lc); }
.LBB0_108:
	s_add_i32 s27, s4, s72
	v_add_u32_e32 v13, 0x2080, v16
	s_cmp_gt_i32 s27, 7
	s_barrier
	s_waitcnt vmcnt(2)
	ds_write2_b32 v15, v2, v3 offset1:1
	s_waitcnt vmcnt(1)
	ds_write2_b32 v13, v6, v7 offset1:1
	ds_write2_b32 v15, v4, v5 offset0:2 offset1:3
	v_add_u32_e32 v13, 0x2088, v16
	s_cselect_b64 s[22:23], -1, 0
	s_cmp_lt_i32 s27, 8
	s_mov_b64 s[24:25], -1
	ds_write2_b32 v13, v8, v9 offset1:1
	s_cbranch_scc1 .LBB0_110
	s_add_i32 s40, s26, s74
	s_mov_b64 s[24:25], 0

; __device__ __forceinline__ int tid_v() { int t = threadIdx.x; asm volatile("" : "+v"(t)); return t; }
; __device__ __forceinline__ int bid_s() { int b = blockIdx.x; asm volatile("" : "+s"(b)); return b; }
; __device__ __forceinline__ void tconv(const float* __restrict__ src, bf16_t* __restrict__ dst, int K, int N, const float* __restrict__ scale, float* tile, int& rot) {
;     const int tk = K >> 6, tn = N >> 6, nt = tk * tn, G = gridDim.x;
;     const int tid = tid_v(), lr = tid >> 4, lc = (tid & 15) * 4;
;     const int sn = tid >> 3, sk = (tid & 7) * 8;
;     int t = (int)((bid_s() + G - (rot % G)) % G);
;     f32x4 v0, v1;
;     if (t < nt) { const int kt = t / tn, k0 = kt << 6, n0 = (t - kt * tn) << 6; v0 = *(const f32x4*)(src + (size_t)(k0 + lr) * N + n0 + lc); v1 = *(const f32x4*)(src + (size_t)(k0 + lr + 32) * N + n0 + lc); }
; __device__ __forceinline__ void phase0(unsigned char* shm) {
;     ...
;         tconv(IN(10) + (size_t)l * 64 * 512, W + oA2, 64, 512, nullptr, tile, rot);
.LBB0_112:
	s_add_i32 s20, s39, 0x1558
	s_mul_hi_u32 s21, s20, s36
	v_mov_b32_e32 v12, v179
	s_mov_b32 s4, s87
	s_mul_i32 s21, s21, s29
	s_load_dwordx2 s[18:19], s[0:1], 0x50
	s_waitcnt lgkmcnt(0)
	s_sub_i32 s20, s20, s21
	s_add_i32 s4, s4, s72
	s_sub_i32 s21, s20, s29
	s_cmp_ge_u32 s20, s29
	s_cselect_b32 s20, s21, s20
	s_sub_i32 s21, s20, s29
	s_cmp_ge_u32 s20, s29
	s_cselect_b32 s20, s21, s20
	s_sub_i32 s4, s4, s20
	s_ashr_i32 s20, s4, 31
	s_abs_i32 s4, s4
	s_mul_hi_u32 s21, s4, s36
	s_mul_i32 s21, s21, s29
	s_sub_i32 s4, s4, s21
	s_sub_i32 s21, s4, s29
	s_cmp_ge_u32 s4, s29
	s_cselect_b32 s4, s21, s4
	s_sub_i32 s21, s4, s29
	s_cmp_ge_u32 s4, s29
	s_cselect_b32 s4, s21, s4
	s_xor_b32 s21, s4, s20
	s_sub_i32 s4, s21, s20
	s_cmp_gt_i32 s4, 7
	s_cbranch_scc1 .LBB0_119
	s_lshl_b64 s[12:13], s[12:13], 2
	s_add_u32 s12, s18, s12
	s_addc_u32 s13, s19, s13
	s_add_u32 s18, s10, 0x2ab0000
	s_addc_u32 s19, s11, 0
	s_ashr_i32 s22, s4, 31
	s_lshr_b32 s22, s22, 29
	s_add_i32 s22, s4, s22
	v_ashrrev_i32_e32 v1, 4, v12
	s_waitcnt vmcnt(2)
	v_lshlrev_b32_e32 v2, 2, v12
	s_ashr_i32 s23, s22, 3
	v_and_b32_e32 v20, 60, v2
	v_lshl_add_u32 v2, s23, 6, v1
	s_lshl_b32 s22, s23, 9
	s_lshl_b32 s24, s4, 6
	v_ashrrev_i32_e32 v3, 31, v2
	s_sub_i32 s22, s24, s22
	v_lshlrev_b64 v[2:3], 11, v[2:3]
	v_lshl_add_u64 v[2:3], s[12:13], 0, v[2:3]
	s_ashr_i32 s23, s22, 31
	v_lshl_add_u64 v[2:3], s[22:23], 2, v[2:3]
	v_lshlrev_b32_e32 v10, 2, v20
	v_lshl_add_u64 v[14:15], v[2:3], 0, v[10:11]
	v_add_co_u32_e32 v16, vcc, s38, v14
	s_lshl_b32 s21, s21, 6
	s_nop 0
	v_addc_co_u32_e32 v17, vcc, 0, v15, vcc
	global_load_dwordx4 v[2:5], v[14:15], off
	global_load_dwordx4 v[6:9], v[16:17], off
	global_load_dword v52, v[14:15], off
	v_ashrrev_i32_e32 v14, 3, v12
	v_lshlrev_b32_e32 v12, 3, v12
	v_and_b32_e32 v22, 56, v12
	v_mul_lo_u32 v12, v1, s31
	v_add3_u32 v15, 0, v10, v12
	v_add3_u32 v16, 0, v12, v10
	v_mul_u32_u24_e32 v12, 0x41, v22
	v_lshlrev_b32_e32 v10, 2, v14
	v_lshlrev_b32_e32 v12, 2, v12
	s_lshl_b32 s20, s20, 6
	v_add3_u32 v17, 0, v10, v12
	v_add3_u32 v18, 0, v12, v10
	s_sub_i32 s24, s21, s20
	v_lshlrev_b32_e32 v12, 2, v20
	v_lshlrev_b32_e32 v10, 1, v22
	s_branch .LBB0_115

; __device__ __forceinline__ void tconv(const float* __restrict__ src, bf16_t* __restrict__ dst, int K, int N, const float* __restrict__ scale, float* tile, int& rot) {
;     ...
;         __syncthreads();
; #pragma unroll
;         for (int j = 0; j < 4; ++j) { tile[lr * 65 + lc + j] = v0[j]; tile[(lr + 32) * 65 + lc + j] = v1[j]; }
;         const int t2 = t + G;
;         if (t2 < nt) { const int kt2 = t2 / tn, k2 = kt2 << 6, n2 = (t2 - kt2 * tn) << 6; v0 = *(const f32x4*)(src + (size_t)(k2 + lr) * N + n2 + lc); v1 = *(const f32x4*)(src + (size_t)(k2 + lr + 32) * N + n2 + lc); }
.LBB0_115:
	s_add_i32 s25, s4, s72
	v_add_u32_e32 v13, 0x2080, v16
	s_cmp_gt_i32 s25, 7
	s_barrier
	s_waitcnt vmcnt(2)
	ds_write2_b32 v15, v2, v3 offset1:1
	s_waitcnt vmcnt(1)
	ds_write2_b32 v13, v6, v7 offset1:1
	ds_write2_b32 v15, v4, v5 offset0:2 offset1:3
	v_add_u32_e32 v13, 0x2088, v16
	s_cselect_b64 s[20:21], -1, 0
	s_cmp_lt_i32 s25, 8
	s_mov_b64 s[22:23], -1
	ds_write2_b32 v13, v8, v9 offset1:1
	s_cbranch_scc1 .LBB0_117
	s_add_i32 s26, s24, s74
	s_mov_b64 s[22:23], 0

; __device__ __forceinline__ int tid_v() { int t = threadIdx.x; asm volatile("" : "+v"(t)); return t; }
; __device__ __forceinline__ int bid_s() { int b = blockIdx.x; asm volatile("" : "+s"(b)); return b; }
; __device__ __forceinline__ void tconv(const float* __restrict__ src, bf16_t* __restrict__ dst, int K, int N, const float* __restrict__ scale, float* tile, int& rot) {
;     const int tk = K >> 6, tn = N >> 6, nt = tk * tn, G = gridDim.x;
;     const int tid = tid_v(), lr = tid >> 4, lc = (tid & 15) * 4;
;     const int sn = tid >> 3, sk = (tid & 7) * 8;
;     int t = (int)((bid_s() + G - (rot % G)) % G);
;     f32x4 v0, v1;
;     if (t < nt) { const int kt = t / tn, k0 = kt << 6, n0 = (t - kt * tn) << 6; v0 = *(const f32x4*)(src + (size_t)(k0 + lr) * N + n0 + lc); v1 = *(const f32x4*)(src + (size_t)(k0 + lr + 32) * N + n0 + lc); }
; __device__ __forceinline__ void phase0(unsigned char* shm) {
;     ...
;         tconv(IN(11) + (size_t)l * 128 * 512, W + oG2, 128, 512, nullptr, tile, rot);
.LBB0_119:
	s_add_i32 s18, s39, 0x1560
	s_mul_hi_u32 s19, s18, s36
	v_mov_b32_e32 v12, v179
	s_mov_b32 s4, s87
	s_mul_i32 s19, s19, s29
	s_load_dwordx2 s[12:13], s[0:1], 0x58
	s_waitcnt lgkmcnt(0)
	s_sub_i32 s18, s18, s19
	s_add_i32 s4, s4, s72
	s_sub_i32 s19, s18, s29
	s_cmp_ge_u32 s18, s29
	s_cselect_b32 s18, s19, s18
	s_sub_i32 s19, s18, s29
	s_cmp_ge_u32 s18, s29
	s_cselect_b32 s18, s19, s18
	s_sub_i32 s4, s4, s18
	s_ashr_i32 s18, s4, 31
	s_abs_i32 s4, s4
	s_mul_hi_u32 s19, s4, s36
	s_mul_i32 s19, s19, s29
	s_sub_i32 s4, s4, s19
	s_sub_i32 s19, s4, s29
	s_cmp_ge_u32 s4, s29
	s_cselect_b32 s4, s19, s4
	s_sub_i32 s19, s4, s29
	s_cmp_ge_u32 s4, s29
	s_cselect_b32 s4, s19, s4
	s_xor_b32 s19, s4, s18
	s_sub_i32 s4, s19, s18
	s_cmp_gt_i32 s4, 15
	s_cbranch_scc1 .LBB0_6
	s_lshl_b64 s[2:3], s[2:3], 18
	s_add_u32 s2, s12, s2
	s_addc_u32 s3, s13, s3
	s_add_u32 s10, s10, 0x2ac0000
	s_addc_u32 s11, s11, 0
	s_ashr_i32 s12, s4, 31
	s_lshr_b32 s12, s12, 29
	s_add_i32 s12, s4, s12
	v_ashrrev_i32_e32 v1, 4, v12
	s_waitcnt vmcnt(2)
	v_lshlrev_b32_e32 v2, 2, v12
	s_ashr_i32 s13, s12, 3
	v_and_b32_e32 v20, 60, v2
	v_lshl_add_u32 v2, s13, 6, v1
	s_lshl_b32 s12, s13, 9
	s_lshl_b32 s20, s4, 6
	v_ashrrev_i32_e32 v3, 31, v2
	s_sub_i32 s12, s20, s12
	v_lshlrev_b64 v[2:3], 11, v[2:3]
	v_lshl_add_u64 v[2:3], s[2:3], 0, v[2:3]
	s_ashr_i32 s13, s12, 31
	v_lshl_add_u64 v[2:3], s[12:13], 2, v[2:3]
	v_lshlrev_b32_e32 v10, 2, v20
	v_lshl_add_u64 v[14:15], v[2:3], 0, v[10:11]
	v_add_co_u32_e32 v16, vcc, s38, v14
	s_lshl_b32 s12, s19, 6
	s_nop 0
	v_addc_co_u32_e32 v17, vcc, 0, v15, vcc
	global_load_dwordx4 v[2:5], v[14:15], off
	global_load_dwordx4 v[6:9], v[16:17], off
	global_load_dword v52, v[14:15], off
	v_ashrrev_i32_e32 v14, 3, v12
	v_lshlrev_b32_e32 v12, 3, v12
	v_and_b32_e32 v22, 56, v12
	v_mul_lo_u32 v12, v1, s31
	v_add3_u32 v15, 0, v10, v12
	v_add3_u32 v16, 0, v12, v10
	v_mul_u32_u24_e32 v12, 0x41, v22
	v_lshlrev_b32_e32 v10, 2, v14
	v_lshlrev_b32_e32 v12, 2, v12
	s_lshl_b32 s13, s18, 6
	v_add3_u32 v17, 0, v10, v12
	v_add3_u32 v18, 0, v12, v10
	s_sub_i32 s20, s12, s13
	v_lshlrev_b32_e32 v12, 2, v20
	v_lshlrev_b32_e32 v10, 1, v22
	s_branch .LBB0_122

; __device__ __forceinline__ void tconv(const float* __restrict__ src, bf16_t* __restrict__ dst, int K, int N, const float* __restrict__ scale, float* tile, int& rot) {
;     ...
;         __syncthreads();
; #pragma unroll
;         for (int j = 0; j < 4; ++j) { tile[lr * 65 + lc + j] = v0[j]; tile[(lr + 32) * 65 + lc + j] = v1[j]; }
;         const int t2 = t + G;
;         if (t2 < nt) { const int kt2 = t2 / tn, k2 = kt2 << 6, n2 = (t2 - kt2 * tn) << 6; v0 = *(const f32x4*)(src + (size_t)(k2 + lr) * N + n2 + lc); v1 = *(const f32x4*)(src + (size_t)(k2 + lr + 32) * N + n2 + lc); }
.LBB0_122:
	s_add_i32 s21, s4, s72
	v_add_u32_e32 v13, 0x2080, v16
	s_cmp_gt_i32 s21, 15
	s_barrier
	s_waitcnt vmcnt(2)
	ds_write2_b32 v15, v2, v3 offset1:1
	s_waitcnt vmcnt(1)
	ds_write2_b32 v13, v6, v7 offset1:1
	ds_write2_b32 v15, v4, v5 offset0:2 offset1:3
	v_add_u32_e32 v13, 0x2088, v16
	s_cselect_b64 s[12:13], -1, 0
	s_cmp_lt_i32 s21, 16
	s_mov_b64 s[18:19], -1
	ds_write2_b32 v13, v8, v9 offset1:1
	s_cbranch_scc1 .LBB0_124
	s_add_i32 s22, s20, s74
	s_mov_b64 s[18:19], 0

; __device__ __forceinline__ int tid_v() { int t = threadIdx.x; asm volatile("" : "+v"(t)); return t; }
; __device__ __forceinline__ int bid_s() { int b = blockIdx.x; asm volatile("" : "+s"(b)); return b; }
; #define OUTP() ((float*)karg_ptr<34 * 8>())
; #define WSP() ((unsigned char*)karg_ptr<35 * 8>())
; __device__ __forceinline__ void phase0(unsigned char* shm) {
;     ...
;     __syncthreads();
; }
; __device__ __forceinline__ void phaseX(int l, int s) {
;     const Bufs B = make_bufs(WSP(), l);
;     const float* xin = l == 0 ? IN(0) : OUTP();
;     const float* pin = IN(1) + (size_t)l * 32768 * 256;
;     const int lane = tid_v() & 63, gw = bid_s() * 8 + (tid_v() >> 6);
;     for (int mb = gw; mb < MS; mb += 4096) {
;         f32x4 v[2][4], pv[2]; size_t rg[2];
; #pragma unroll
;         for (int u = 0; u < 2; ++u) { const int m = mb + 2048 * u; rg[u] = (size_t)((m >> 11) * 4096 + s * 2048 + (m & 2047)); const f32x4* xr = (const f32x4*)(xin + rg[u] * 1024);
; #pragma unroll
;             for (int i = 0; i < 4; ++i) v[u][i] = xr[lane + 64 * i];
;             pv[u] = *(const f32x4*)(pin + rg[u] * 256 + lane * 4); }
.LBB0_126:
	s_waitcnt vmcnt(0)
	s_barrier
	s_load_dwordx2 s[2:3], s[0:1], 0x118
	s_waitcnt lgkmcnt(0)
	s_load_dwordx2 s[12:13], s[0:1], 0
	s_waitcnt lgkmcnt(0)
	s_waitcnt vmcnt(2)
	v_mov_b32_e32 v3, v179
	s_mov_b32 s18, s87
	v_mov_b32_e32 v1, v179
	s_load_dwordx2 s[4:5], s[0:1], 8
	s_waitcnt lgkmcnt(0)
	s_lshl_b32 s10, s18, 3
	s_movk_i32 s8, 0x4000
	v_ashrrev_i32_e32 v2, 6, v1
	v_add_u32_e32 v44, s10, v2
	v_cmp_gt_i32_e32 vcc, s8, v44
	v_mbcnt_lo_u32_b32 v1, -1, 0
	s_and_saveexec_b64 s[8:9], vcc
	s_cbranch_execz .LBB0_133
	v_mbcnt_hi_u32_b32 v4, -1, v1
	v_and_b32_e32 v5, 64, v4
	v_add_u32_e32 v5, 64, v5
	s_waitcnt vmcnt(1)
	v_xor_b32_e32 v6, 32, v4
	v_cmp_lt_i32_e32 vcc, v6, v5
	v_and_b32_e32 v3, 63, v3
	v_lshlrev_b32_e32 v26, 4, v3
	v_cndmask_b32_e32 v6, v4, v6, vcc
	v_lshlrev_b32_e32 v45, 2, v6
	v_xor_b32_e32 v6, 16, v4
	v_cmp_lt_i32_e32 vcc, v6, v5
	v_mov_b32_e32 v27, 0
	v_lshl_add_u64 v[28:29], s[4:5], 0, v[26:27]
	v_cndmask_b32_e32 v6, v4, v6, vcc
	v_lshlrev_b32_e32 v46, 2, v6
	v_xor_b32_e32 v6, 8, v4
	v_cmp_lt_i32_e32 vcc, v6, v5
	v_cmp_eq_u32_e64 s[4:5], 0, v3
	v_lshlrev_b32_e32 v8, 3, v3
	v_cndmask_b32_e32 v6, v4, v6, vcc
	v_lshlrev_b32_e32 v47, 2, v6
	v_xor_b32_e32 v6, 4, v4
	v_cmp_lt_i32_e32 vcc, v6, v5
	v_ashrrev_i32_e32 v3, 31, v2
	s_ashr_i32 s11, s10, 31
	v_cndmask_b32_e32 v6, v4, v6, vcc
	v_lshlrev_b32_e32 v48, 2, v6
	v_xor_b32_e32 v6, 2, v4
	v_cmp_lt_i32_e32 vcc, v6, v5
	v_lshl_add_u64 v[30:31], s[12:13], 0, v[26:27]
	s_mov_b64 s[12:13], 0x7600000
	v_cndmask_b32_e32 v6, v4, v6, vcc
	v_lshlrev_b32_e32 v49, 2, v6
	v_xor_b32_e32 v6, 1, v4
	v_cmp_lt_i32_e32 vcc, v6, v5
	s_movk_i32 s24, 0xf000
	v_mov_b32_e32 v51, 0x358637bd
	v_cndmask_b32_e32 v4, v4, v6, vcc
	v_lshlrev_b32_e32 v50, 2, v4
	v_add_u32_e32 v4, 0x800, v44
	v_ashrrev_i32_e32 v5, 31, v4
	v_lshlrev_b64 v[6:7], 9, v[4:5]
	v_lshlrev_b64 v[32:33], 2, v[4:5]
	v_or_b32_e32 v6, v6, v8
	v_lshlrev_b64 v[36:37], 11, v[4:5]
	v_lshl_add_u64 v[4:5], v[2:3], 0, s[10:11]
	v_lshlrev_b32_e32 v2, 1, v2
	v_lshl_add_u64 v[34:35], v[6:7], 0, s[12:13]
	v_lshlrev_b64 v[6:7], 9, v[4:5]
	v_lshl_add_u32 v26, s18, 4, v2
	v_lshlrev_b64 v[2:3], 11, v[4:5]
	v_or_b32_e32 v6, v6, v8
	v_or_b32_e32 v2, v2, v8
	s_mov_b64 s[10:11], 0x5600400
	v_or_b32_e32 v36, v36, v8
	v_lshlrev_b64 v[38:39], 2, v[4:5]
	v_lshl_add_u64 v[40:41], v[6:7], 0, s[12:13]
	v_lshl_add_u64 v[42:43], v[2:3], 0, s[10:11]
	s_mov_b64 s[10:11], 0
	s_mov_b32 s25, 0x800000
	s_mov_b32 s26, 0x5600000
	s_mov_b64 s[12:13], 0x4000
	s_mov_b64 s[18:19], 0x200000
	s_mov_b64 s[20:21], 0x800000
	s_movk_i32 s27, 0x2fff
	s_branch .LBB0_129

; __global__ void __launch_bounds__(512, 2) mega(Params p) {
	.amdhsa_kernel _Z4mega6Params
		.amdhsa_group_segment_fixed_size 0
		.amdhsa_private_segment_fixed_size 0
		.amdhsa_kernarg_size 544
		.amdhsa_user_sgpr_count 2
		.amdhsa_user_sgpr_dispatch_ptr 0
		.amdhsa_user_sgpr_queue_ptr 0
		.amdhsa_user_sgpr_kernarg_segment_ptr 1
		.amdhsa_user_sgpr_dispatch_id 0
		.amdhsa_user_sgpr_kernarg_preload_length 0
		.amdhsa_user_sgpr_kernarg_preload_offset 0
		.amdhsa_user_sgpr_private_segment_size 0
		.amdhsa_uses_dynamic_stack 0
		.amdhsa_enable_private_segment 0
		.amdhsa_system_sgpr_workgroup_id_x 1
		.amdhsa_system_sgpr_workgroup_id_y 0
		.amdhsa_system_sgpr_workgroup_id_z 0
		.amdhsa_system_sgpr_workgroup_info 0
		.amdhsa_system_vgpr_workitem_id 2
		.amdhsa_next_free_vgpr 256
		.amdhsa_next_free_sgpr 102
		.amdhsa_accum_offset 256
		.amdhsa_reserve_vcc 1
		.amdhsa_float_round_mode_32 0
		.amdhsa_float_round_mode_16_64 0
		.amdhsa_float_denorm_mode_32 3
		.amdhsa_float_denorm_mode_16_64 3
		.amdhsa_dx10_clamp 1
		.amdhsa_ieee_mode 1
		.amdhsa_fp16_overflow 0
		.amdhsa_tg_split 0
		.amdhsa_exception_fp_ieee_invalid_op 0
		.amdhsa_exception_fp_denorm_src 0
		.amdhsa_exception_fp_ieee_div_zero 0
		.amdhsa_exception_fp_ieee_overflow 0
		.amdhsa_exception_fp_ieee_underflow 0
		.amdhsa_exception_fp_ieee_inexact 0
		.amdhsa_exception_int_div_zero 0
	.end_amdhsa_kernel
